# GEMM K-loops: LDS-DMA staging rebalanced 2/6/2/6 -> 4/4/4/4 per load segment (As[b][0] restage deferred to next SP1, SP2 waits vmcnt(6))
# speedup vs baseline: 1.0063x; 1.0063x over previous
; #define PG8_STAGE(bufoff, gbase, voff) do { _Pragma("unroll") for (int _i = 0; _i < 2; ++_i) \
;         __builtin_amdgcn_global_load_lds((const unsigned*)((const char*)(gbase) + (voff)[_i]), (PG8_LAS unsigned*)(lds + (bufoff) + ldsw + _i * 8192), 16, 0, 0); } while (0)
; #define PG8_LDA(dst, b, h) do { _Pragma("unroll") for (int m = 0; m < 4; ++m) _Pragma("unroll") for (int k = 0; k < 2; ++k) dst[m][k] = *(const PG8_LAS bf16x8*)(lds + PG8_SA(b, h) + aoff + m * 2048 + k * 1024); } while (0)
; #define PG8_LDB(dst, b, h) do { _Pragma("unroll") for (int n = 0; n < 2; ++n) _Pragma("unroll") for (int k = 0; k < 2; ++k) dst[n][k] = *(const PG8_LAS bf16x8*)(lds + PG8_SB(b, h) + boff + n * 2048 + k * 1024); } while (0)
; #define PG8_MMA(ai, bj, At, Bt) do { __builtin_amdgcn_s_setprio(1); _Pragma("unroll") for (int m = 0; m < 4; ++m) _Pragma("unroll") for (int n = 0; n < 2; ++n) _Pragma("unroll") for (int k = 0; k < 2; ++k) \
;         acc[ai][bj][m][n] = __builtin_amdgcn_mfma_f32_16x16x32_bf16(Bt[n][k], At[m][k], acc[ai][bj][m][n], 0, 0, 0); __builtin_amdgcn_s_setprio(0); } while (0)
; #define PG8_WAIT_V(n) asm volatile("s_waitcnt vmcnt(" #n ")" ::: "memory")
; #define PG8_WAIT_L(n) asm volatile("s_waitcnt lgkmcnt(" #n ")" ::: "memory")
; #define PG8_BAR __builtin_amdgcn_s_barrier()
; #define PG8_SCHED __builtin_amdgcn_sched_barrier(0)
; template <class Epi, class Sched, bool ALIGN_EPI = false, bool SP2 = false>
; __device__ __forceinline__ void gemm_phase(PG8_LAS unsigned char* lds, const Gemm g, const Sched& S, const Epi& E) {
;     ...
;             PG8_LDB(B0, 0, 0); PG8_LDB(B1, 0, 1); PG8_SCHED; PG8_LDA(At, 0, 0); PG8_STAGE(PG8_SA(1, 1), a1 + hstep, voffA);
;             PG8_WAIT_V(8); PG8_WAIT_L(0); PG8_BAR; PG8_MMA(0, 0, At, B0); PG8_MMA(0, 1, At, B1); PG8_BAR; PG8_SCHED;
;             PG8_LDA(At, 0, 1); PG8_STAGE(PG8_SB(0, 0), b2, voffB); PG8_STAGE(PG8_SB(0, 1), b2 + hstep, voffB); PG8_STAGE(PG8_SA(0, 0), a2, voffA);
;             PG8_WAIT_V(8); PG8_WAIT_L(0); PG8_BAR; PG8_MMA(1, 0, At, B0); PG8_MMA(1, 1, At, B1); PG8_BAR; PG8_SCHED;
.LBB0_139:
	s_add_u32 s36, s30, 0xfff80080
	s_addc_u32 s37, s31, -1
	s_add_i32 s70, 0, 0x10000
	s_cmp_eq_u32 s69, 28
	s_cselect_b32 s39, s25, s37
	s_cselect_b32 s38, s45, s36
	v_add_u32_e32 v142, s70, v148
	s_cselect_b32 s37, s23, s68
	s_cselect_b32 s36, s66, s67
	s_add_i32 s75, 0, 0x14000
	ds_read_b128 v[152:155], v142
	ds_read_b128 v[166:169], v142 offset:1024
	ds_read_b128 v[170:173], v142 offset:2048
	ds_read_b128 v[174:177], v142 offset:3072
	v_add_u32_e32 v142, s75, v148
	ds_read_b128 v[178:181], v142
	ds_read_b128 v[182:185], v142 offset:1024
	ds_read_b128 v[186:189], v142 offset:2048
	ds_read_b128 v[190:193], v142 offset:3072
	s_add_u32 s98, s30, 0xfff80000
	s_addc_u32 s99, s31, -1
	v_lshl_add_u64 v[144:145], s[98:99], 0, v[138:139]
	s_mov_b32 m0, s57
	s_nop 0
	global_load_lds_dwordx4 v[144:145], off
	v_lshl_add_u64 v[144:145], s[98:99], 0, v[140:141]
	s_mov_b32 m0, s58
	s_nop 0
	global_load_lds_dwordx4 v[144:145], off
	v_lshl_add_u64 v[144:145], s[30:31], 0, v[138:139]
	s_add_i32 m0, s53, 0xc000
	ds_read_b128 v[200:203], v151
	ds_read_b128 v[204:207], v151 offset:1024
	ds_read_b128 v[208:211], v151 offset:2048
	ds_read_b128 v[212:215], v151 offset:3072
	ds_read_b128 v[216:219], v151 offset:4096
	ds_read_b128 v[220:223], v151 offset:5120
	ds_read_b128 v[224:227], v151 offset:6144
	ds_read_b128 v[228:231], v151 offset:7168
	global_load_lds_dwordx4 v[144:145], off
	v_lshl_add_u64 v[144:145], s[30:31], 0, v[140:141]
	s_add_i32 m0, s53, 0xe000
	s_nop 0
	global_load_lds_dwordx4 v[144:145], off
	s_waitcnt vmcnt(8)
	s_waitcnt lgkmcnt(0)
	s_barrier
	s_setprio 1
	s_waitcnt lgkmcnt(0)
	v_mfma_f32_16x16x32_bf16 v[126:129], v[152:155], v[200:203], v[126:129]
	v_mfma_f32_16x16x32_bf16 v[122:125], v[170:173], v[200:203], v[122:125]
	v_mfma_f32_16x16x32_bf16 v[110:113], v[152:155], v[208:211], v[110:113]
	v_mfma_f32_16x16x32_bf16 v[106:109], v[170:173], v[208:211], v[106:109]
	v_mfma_f32_16x16x32_bf16 v[94:97], v[152:155], v[216:219], v[94:97]
	v_mfma_f32_16x16x32_bf16 v[90:93], v[170:173], v[216:219], v[90:93]
	v_mfma_f32_16x16x32_bf16 v[78:81], v[152:155], v[224:227], v[78:81]
	v_mfma_f32_16x16x32_bf16 v[74:77], v[170:173], v[224:227], v[74:77]
	v_mfma_f32_16x16x32_bf16 v[126:129], v[166:169], v[204:207], v[126:129]
	v_mfma_f32_16x16x32_bf16 v[122:125], v[174:177], v[204:207], v[122:125]
	v_mfma_f32_16x16x32_bf16 v[110:113], v[166:169], v[212:215], v[110:113]
	v_mfma_f32_16x16x32_bf16 v[106:109], v[174:177], v[212:215], v[106:109]
	v_mfma_f32_16x16x32_bf16 v[94:97], v[166:169], v[220:223], v[94:97]
	v_mfma_f32_16x16x32_bf16 v[90:93], v[174:177], v[220:223], v[90:93]
	v_mfma_f32_16x16x32_bf16 v[78:81], v[166:169], v[228:231], v[78:81]
	v_mfma_f32_16x16x32_bf16 v[74:77], v[174:177], v[228:231], v[74:77]
	s_setprio 0
	s_setprio 1
	v_mfma_f32_16x16x32_bf16 v[118:121], v[178:181], v[200:203], v[118:121]
	v_mfma_f32_16x16x32_bf16 v[114:117], v[186:189], v[200:203], v[114:117]
	v_mfma_f32_16x16x32_bf16 v[102:105], v[178:181], v[208:211], v[102:105]
	v_mfma_f32_16x16x32_bf16 v[98:101], v[186:189], v[208:211], v[98:101]
	v_mfma_f32_16x16x32_bf16 v[86:89], v[178:181], v[216:219], v[86:89]
	v_mfma_f32_16x16x32_bf16 v[82:85], v[186:189], v[216:219], v[82:85]
	v_mfma_f32_16x16x32_bf16 v[70:73], v[178:181], v[224:227], v[70:73]
	v_mfma_f32_16x16x32_bf16 v[66:69], v[186:189], v[224:227], v[66:69]
	v_mfma_f32_16x16x32_bf16 v[118:121], v[182:185], v[204:207], v[118:121]
	v_mfma_f32_16x16x32_bf16 v[114:117], v[190:193], v[204:207], v[114:117]
	v_mfma_f32_16x16x32_bf16 v[102:105], v[182:185], v[212:215], v[102:105]
	v_mfma_f32_16x16x32_bf16 v[98:101], v[190:193], v[212:215], v[98:101]
	v_mfma_f32_16x16x32_bf16 v[86:89], v[182:185], v[220:223], v[86:89]
	v_mfma_f32_16x16x32_bf16 v[82:85], v[190:193], v[220:223], v[82:85]
	v_mfma_f32_16x16x32_bf16 v[70:73], v[182:185], v[228:231], v[70:73]
	v_mfma_f32_16x16x32_bf16 v[66:69], v[190:193], v[228:231], v[66:69]
	s_setprio 0
	s_barrier
	s_add_i32 s70, s70, s52
	v_lshl_add_u64 v[144:145], s[36:37], 0, v[158:159]
	s_mov_b32 m0, s70
	ds_read_b128 v[200:203], v151 offset:16384
	ds_read_b128 v[204:207], v151 offset:17408
	ds_read_b128 v[208:211], v151 offset:18432
	ds_read_b128 v[212:215], v151 offset:19456
	ds_read_b128 v[216:219], v151 offset:20480
	ds_read_b128 v[220:223], v151 offset:21504
	ds_read_b128 v[224:227], v151 offset:22528
	ds_read_b128 v[228:231], v151 offset:23552
	global_load_lds_dwordx4 v[144:145], off
	s_add_i32 m0, s70, 0x2000
	s_add_u32 s70, s36, 0x80000
	v_lshl_add_u64 v[156:157], s[36:37], 0, v[134:135]
	s_addc_u32 s71, s37, 0
	s_add_i32 s75, s75, s52
	global_load_lds_dwordx4 v[156:157], off
	v_lshl_add_u64 v[162:163], s[70:71], 0, v[158:159]
	s_mov_b32 m0, s75
	v_lshl_add_u64 v[164:165], s[38:39], 0, v[132:133]
	global_load_lds_dwordx4 v[162:163], off
	v_lshl_add_u64 v[162:163], s[70:71], 0, v[134:135]
	s_add_i32 m0, s75, 0x2000
	s_nop 0
	global_load_lds_dwordx4 v[162:163], off
	v_lshl_add_u64 v[162:163], s[38:39], 0, v[130:131]
	s_waitcnt vmcnt(6)
	s_waitcnt lgkmcnt(0)
	s_barrier
; #define PG8_STAGE(bufoff, gbase, voff) do { _Pragma("unroll") for (int _i = 0; _i < 2; ++_i) \
;         __builtin_amdgcn_global_load_lds((const unsigned*)((const char*)(gbase) + (voff)[_i]), (PG8_LAS unsigned*)(lds + (bufoff) + ldsw + _i * 8192), 16, 0, 0); } while (0)
; #define PG8_LDA(dst, b, h) do { _Pragma("unroll") for (int m = 0; m < 4; ++m) _Pragma("unroll") for (int k = 0; k < 2; ++k) dst[m][k] = *(const PG8_LAS bf16x8*)(lds + PG8_SA(b, h) + aoff + m * 2048 + k * 1024); } while (0)
; #define PG8_LDB(dst, b, h) do { _Pragma("unroll") for (int n = 0; n < 2; ++n) _Pragma("unroll") for (int k = 0; k < 2; ++k) dst[n][k] = *(const PG8_LAS bf16x8*)(lds + PG8_SB(b, h) + boff + n * 2048 + k * 1024); } while (0)
; #define PG8_MMA(ai, bj, At, Bt) do { __builtin_amdgcn_s_setprio(1); _Pragma("unroll") for (int m = 0; m < 4; ++m) _Pragma("unroll") for (int n = 0; n < 2; ++n) _Pragma("unroll") for (int k = 0; k < 2; ++k) \
;         acc[ai][bj][m][n] = __builtin_amdgcn_mfma_f32_16x16x32_bf16(Bt[n][k], At[m][k], acc[ai][bj][m][n], 0, 0, 0); __builtin_amdgcn_s_setprio(0); } while (0)
; #define PG8_WAIT_V(n) asm volatile("s_waitcnt vmcnt(" #n ")" ::: "memory")
; #define PG8_WAIT_L(n) asm volatile("s_waitcnt lgkmcnt(" #n ")" ::: "memory")
; #define PG8_BAR __builtin_amdgcn_s_barrier()
; #define PG8_SCHED __builtin_amdgcn_sched_barrier(0)
; template <class Epi, class Sched, bool ALIGN_EPI = false, bool SP2 = false>
; __device__ __forceinline__ void gemm_phase(PG8_LAS unsigned char* lds, const Gemm g, const Sched& S, const Epi& E) {
;     ...
;             PG8_WAIT_V(8); PG8_WAIT_L(0); PG8_BAR; PG8_MMA(1, 0, At, B0); PG8_MMA(1, 1, At, B1); PG8_BAR; PG8_SCHED;
;             PG8_LDB(B0, 1, 0); PG8_LDB(B1, 1, 1); PG8_SCHED; PG8_LDA(At, 1, 0); PG8_STAGE(PG8_SA(0, 1), a2 + hstep, voffA);
;             PG8_WAIT_V(8); PG8_WAIT_L(0); PG8_BAR; PG8_MMA(0, 0, At, B0); PG8_MMA(0, 1, At, B1); PG8_BAR; PG8_SCHED;
	s_setprio 1
	s_waitcnt lgkmcnt(0)
	v_mfma_f32_16x16x32_bf16 v[62:65], v[152:155], v[200:203], v[62:65]
	v_mfma_f32_16x16x32_bf16 v[58:61], v[170:173], v[200:203], v[58:61]
	v_mfma_f32_16x16x32_bf16 v[46:49], v[152:155], v[208:211], v[46:49]
	v_mfma_f32_16x16x32_bf16 v[42:45], v[170:173], v[208:211], v[42:45]
	v_mfma_f32_16x16x32_bf16 v[30:33], v[152:155], v[216:219], v[30:33]
	v_mfma_f32_16x16x32_bf16 v[26:29], v[170:173], v[216:219], v[26:29]
	v_mfma_f32_16x16x32_bf16 v[14:17], v[152:155], v[224:227], v[14:17]
	v_mfma_f32_16x16x32_bf16 v[10:13], v[170:173], v[224:227], v[10:13]
	v_mfma_f32_16x16x32_bf16 v[62:65], v[166:169], v[204:207], v[62:65]
	v_mfma_f32_16x16x32_bf16 v[58:61], v[174:177], v[204:207], v[58:61]
	v_mfma_f32_16x16x32_bf16 v[46:49], v[166:169], v[212:215], v[46:49]
	v_mfma_f32_16x16x32_bf16 v[42:45], v[174:177], v[212:215], v[42:45]
	v_mfma_f32_16x16x32_bf16 v[30:33], v[166:169], v[220:223], v[30:33]
	v_mfma_f32_16x16x32_bf16 v[26:29], v[174:177], v[220:223], v[26:29]
	v_mfma_f32_16x16x32_bf16 v[14:17], v[166:169], v[228:231], v[14:17]
	v_mfma_f32_16x16x32_bf16 v[10:13], v[174:177], v[228:231], v[10:13]
	s_setprio 0
	s_setprio 1
	v_mfma_f32_16x16x32_bf16 v[54:57], v[178:181], v[200:203], v[54:57]
	v_mfma_f32_16x16x32_bf16 v[50:53], v[186:189], v[200:203], v[50:53]
	v_mfma_f32_16x16x32_bf16 v[38:41], v[178:181], v[208:211], v[38:41]
	v_mfma_f32_16x16x32_bf16 v[34:37], v[186:189], v[208:211], v[34:37]
	v_mfma_f32_16x16x32_bf16 v[22:25], v[178:181], v[216:219], v[22:25]
	v_mfma_f32_16x16x32_bf16 v[18:21], v[186:189], v[216:219], v[18:21]
	v_mfma_f32_16x16x32_bf16 v[6:9], v[178:181], v[224:227], v[6:9]
	v_mfma_f32_16x16x32_bf16 v[2:5], v[186:189], v[224:227], v[2:5]
	v_mfma_f32_16x16x32_bf16 v[54:57], v[182:185], v[204:207], v[54:57]
	v_mfma_f32_16x16x32_bf16 v[50:53], v[190:193], v[204:207], v[50:53]
	v_mfma_f32_16x16x32_bf16 v[38:41], v[182:185], v[212:215], v[38:41]
	v_mfma_f32_16x16x32_bf16 v[34:37], v[190:193], v[212:215], v[34:37]
	v_mfma_f32_16x16x32_bf16 v[22:25], v[182:185], v[220:223], v[22:25]
	v_mfma_f32_16x16x32_bf16 v[18:21], v[190:193], v[220:223], v[18:21]
	v_mfma_f32_16x16x32_bf16 v[6:9], v[182:185], v[228:231], v[6:9]
	v_mfma_f32_16x16x32_bf16 v[2:5], v[190:193], v[228:231], v[2:5]
	s_setprio 0
	s_barrier
	s_add_i32 s70, 0, 0x18000
	v_add_u32_e32 v142, s70, v148
	s_add_i32 s71, 0, 0x1c000
	ds_read_b128 v[152:155], v142
	ds_read_b128 v[166:169], v142 offset:1024
	ds_read_b128 v[170:173], v142 offset:2048
	ds_read_b128 v[174:177], v142 offset:3072
	v_add_u32_e32 v142, s71, v148
	ds_read_b128 v[178:181], v142
	ds_read_b128 v[182:185], v142 offset:1024
	ds_read_b128 v[186:189], v142 offset:2048
	ds_read_b128 v[190:193], v142 offset:3072
	s_add_u32 s38, s38, 0x80000
	s_addc_u32 s39, s39, 0
	s_mov_b32 m0, s53
	s_nop 0
	global_load_lds_dwordx4 v[162:163], off
	s_mov_b32 m0, s54
	s_nop 0
	global_load_lds_dwordx4 v[164:165], off
	s_mov_b32 m0, s55
	v_lshl_add_u64 v[232:233], s[38:39], 0, v[130:131]
	ds_read_b128 v[200:203], v151 offset:32768
	ds_read_b128 v[204:207], v151 offset:33792
	ds_read_b128 v[208:211], v151 offset:34816
	ds_read_b128 v[212:215], v151 offset:35840
	ds_read_b128 v[216:219], v151 offset:36864
	ds_read_b128 v[220:223], v151 offset:37888
	ds_read_b128 v[224:227], v151 offset:38912
	ds_read_b128 v[228:231], v151 offset:39936
	global_load_lds_dwordx4 v[232:233], off
	v_lshl_add_u64 v[232:233], s[38:39], 0, v[132:133]
	s_mov_b32 m0, s56
	s_nop 0
	global_load_lds_dwordx4 v[232:233], off
	s_waitcnt vmcnt(8)
	s_waitcnt lgkmcnt(0)
	s_barrier
; #define PG8_STAGE(bufoff, gbase, voff) do { _Pragma("unroll") for (int _i = 0; _i < 2; ++_i) \
;         __builtin_amdgcn_global_load_lds((const unsigned*)((const char*)(gbase) + (voff)[_i]), (PG8_LAS unsigned*)(lds + (bufoff) + ldsw + _i * 8192), 16, 0, 0); } while (0)
; #define PG8_LDA(dst, b, h) do { _Pragma("unroll") for (int m = 0; m < 4; ++m) _Pragma("unroll") for (int k = 0; k < 2; ++k) dst[m][k] = *(const PG8_LAS bf16x8*)(lds + PG8_SA(b, h) + aoff + m * 2048 + k * 1024); } while (0)
; #define PG8_MMA(ai, bj, At, Bt) do { __builtin_amdgcn_s_setprio(1); _Pragma("unroll") for (int m = 0; m < 4; ++m) _Pragma("unroll") for (int n = 0; n < 2; ++n) _Pragma("unroll") for (int k = 0; k < 2; ++k) \
;         acc[ai][bj][m][n] = __builtin_amdgcn_mfma_f32_16x16x32_bf16(Bt[n][k], At[m][k], acc[ai][bj][m][n], 0, 0, 0); __builtin_amdgcn_s_setprio(0); } while (0)
; #define PG8_WAIT_V(n) asm volatile("s_waitcnt vmcnt(" #n ")" ::: "memory")
; #define PG8_WAIT_L(n) asm volatile("s_waitcnt lgkmcnt(" #n ")" ::: "memory")
; #define PG8_BAR __builtin_amdgcn_s_barrier()
; #define PG8_SCHED __builtin_amdgcn_sched_barrier(0)
; template <class Epi, class Sched, bool ALIGN_EPI = false, bool SP2 = false>
; __device__ __forceinline__ void gemm_phase(PG8_LAS unsigned char* lds, const Gemm g, const Sched& S, const Epi& E) {
;     ...
;             PG8_WAIT_V(8); PG8_WAIT_L(0); PG8_BAR; PG8_MMA(0, 0, At, B0); PG8_MMA(0, 1, At, B1); PG8_BAR; PG8_SCHED;
;             PG8_LDA(At, 1, 1); PG8_STAGE(PG8_SB(1, 0), b3, voffB); PG8_STAGE(PG8_SB(1, 1), b3 + hstep, voffB); PG8_STAGE(PG8_SA(1, 0), a3, voffA);
;             PG8_WAIT_V(8); PG8_WAIT_L(0); PG8_BAR; PG8_MMA(1, 0, At, B0); PG8_MMA(1, 1, At, B1); PG8_BAR; PG8_SCHED;
	s_setprio 1
	s_waitcnt lgkmcnt(0)
	v_mfma_f32_16x16x32_bf16 v[126:129], v[152:155], v[200:203], v[126:129]
	v_mfma_f32_16x16x32_bf16 v[122:125], v[170:173], v[200:203], v[122:125]
	v_mfma_f32_16x16x32_bf16 v[110:113], v[152:155], v[208:211], v[110:113]
	v_mfma_f32_16x16x32_bf16 v[106:109], v[170:173], v[208:211], v[106:109]
	v_mfma_f32_16x16x32_bf16 v[94:97], v[152:155], v[216:219], v[94:97]
	v_mfma_f32_16x16x32_bf16 v[90:93], v[170:173], v[216:219], v[90:93]
	v_mfma_f32_16x16x32_bf16 v[78:81], v[152:155], v[224:227], v[78:81]
	v_mfma_f32_16x16x32_bf16 v[74:77], v[170:173], v[224:227], v[74:77]
	v_mfma_f32_16x16x32_bf16 v[126:129], v[166:169], v[204:207], v[126:129]
	v_mfma_f32_16x16x32_bf16 v[122:125], v[174:177], v[204:207], v[122:125]
	v_mfma_f32_16x16x32_bf16 v[110:113], v[166:169], v[212:215], v[110:113]
	v_mfma_f32_16x16x32_bf16 v[106:109], v[174:177], v[212:215], v[106:109]
	v_mfma_f32_16x16x32_bf16 v[94:97], v[166:169], v[220:223], v[94:97]
	v_mfma_f32_16x16x32_bf16 v[90:93], v[174:177], v[220:223], v[90:93]
	v_mfma_f32_16x16x32_bf16 v[78:81], v[166:169], v[228:231], v[78:81]
	v_mfma_f32_16x16x32_bf16 v[74:77], v[174:177], v[228:231], v[74:77]
	s_setprio 0
	s_setprio 1
	v_mfma_f32_16x16x32_bf16 v[118:121], v[178:181], v[200:203], v[118:121]
	v_mfma_f32_16x16x32_bf16 v[114:117], v[186:189], v[200:203], v[114:117]
	v_mfma_f32_16x16x32_bf16 v[102:105], v[178:181], v[208:211], v[102:105]
	v_mfma_f32_16x16x32_bf16 v[98:101], v[186:189], v[208:211], v[98:101]
	v_mfma_f32_16x16x32_bf16 v[86:89], v[178:181], v[216:219], v[86:89]
	v_mfma_f32_16x16x32_bf16 v[82:85], v[186:189], v[216:219], v[82:85]
	v_mfma_f32_16x16x32_bf16 v[70:73], v[178:181], v[224:227], v[70:73]
	v_mfma_f32_16x16x32_bf16 v[66:69], v[186:189], v[224:227], v[66:69]
	v_mfma_f32_16x16x32_bf16 v[118:121], v[182:185], v[204:207], v[118:121]
	v_mfma_f32_16x16x32_bf16 v[114:117], v[190:193], v[204:207], v[114:117]
	v_mfma_f32_16x16x32_bf16 v[102:105], v[182:185], v[212:215], v[102:105]
	v_mfma_f32_16x16x32_bf16 v[98:101], v[190:193], v[212:215], v[98:101]
	v_mfma_f32_16x16x32_bf16 v[86:89], v[182:185], v[220:223], v[86:89]
	v_mfma_f32_16x16x32_bf16 v[82:85], v[190:193], v[220:223], v[82:85]
	v_mfma_f32_16x16x32_bf16 v[70:73], v[182:185], v[228:231], v[70:73]
	v_mfma_f32_16x16x32_bf16 v[66:69], v[190:193], v[228:231], v[66:69]
	s_setprio 0
	s_barrier
	s_add_i32 s38, s70, s52
	v_lshl_add_u64 v[144:145], v[144:145], 0, s[10:11]
	s_mov_b32 m0, s38
	ds_read_b128 v[200:203], v151 offset:49152
	ds_read_b128 v[204:207], v151 offset:50176
	ds_read_b128 v[208:211], v151 offset:51200
	ds_read_b128 v[212:215], v151 offset:52224
	ds_read_b128 v[216:219], v151 offset:53248
	ds_read_b128 v[220:223], v151 offset:54272
	ds_read_b128 v[224:227], v151 offset:55296
	ds_read_b128 v[228:231], v151 offset:56320
	global_load_lds_dwordx4 v[144:145], off
	s_add_i32 m0, s38, 0x2000
	s_add_u32 s36, s36, 0x80080
	v_lshl_add_u64 v[144:145], v[156:157], 0, s[10:11]
	s_addc_u32 s37, s37, 0
	s_add_i32 s38, s71, s52
	global_load_lds_dwordx4 v[144:145], off
	v_lshl_add_u64 v[144:145], s[36:37], 0, v[158:159]
	s_mov_b32 m0, s38
	s_nop 0
	global_load_lds_dwordx4 v[144:145], off
	v_lshl_add_u64 v[144:145], s[36:37], 0, v[134:135]
	s_add_i32 m0, s38, 0x2000
	s_nop 0
	global_load_lds_dwordx4 v[144:145], off
	s_waitcnt vmcnt(6)
	s_waitcnt lgkmcnt(0)
	s_barrier
	s_setprio 1
	s_waitcnt lgkmcnt(0)
	v_mfma_f32_16x16x32_bf16 v[62:65], v[152:155], v[200:203], v[62:65]
	v_mfma_f32_16x16x32_bf16 v[58:61], v[170:173], v[200:203], v[58:61]
	v_mfma_f32_16x16x32_bf16 v[46:49], v[152:155], v[208:211], v[46:49]
	v_mfma_f32_16x16x32_bf16 v[42:45], v[170:173], v[208:211], v[42:45]
	v_mfma_f32_16x16x32_bf16 v[30:33], v[152:155], v[216:219], v[30:33]
	v_mfma_f32_16x16x32_bf16 v[26:29], v[170:173], v[216:219], v[26:29]
	v_mfma_f32_16x16x32_bf16 v[14:17], v[152:155], v[224:227], v[14:17]
	v_mfma_f32_16x16x32_bf16 v[10:13], v[170:173], v[224:227], v[10:13]
	v_mfma_f32_16x16x32_bf16 v[62:65], v[166:169], v[204:207], v[62:65]
	v_mfma_f32_16x16x32_bf16 v[58:61], v[174:177], v[204:207], v[58:61]
	v_mfma_f32_16x16x32_bf16 v[46:49], v[166:169], v[212:215], v[46:49]
	v_mfma_f32_16x16x32_bf16 v[42:45], v[174:177], v[212:215], v[42:45]
	v_mfma_f32_16x16x32_bf16 v[30:33], v[166:169], v[220:223], v[30:33]
	v_mfma_f32_16x16x32_bf16 v[26:29], v[174:177], v[220:223], v[26:29]
	v_mfma_f32_16x16x32_bf16 v[14:17], v[166:169], v[228:231], v[14:17]
	v_mfma_f32_16x16x32_bf16 v[10:13], v[174:177], v[228:231], v[10:13]
	s_setprio 0
	s_setprio 1
	v_mfma_f32_16x16x32_bf16 v[54:57], v[178:181], v[200:203], v[54:57]
	v_mfma_f32_16x16x32_bf16 v[50:53], v[186:189], v[200:203], v[50:53]
	v_mfma_f32_16x16x32_bf16 v[38:41], v[178:181], v[208:211], v[38:41]
	v_mfma_f32_16x16x32_bf16 v[34:37], v[186:189], v[208:211], v[34:37]
	v_mfma_f32_16x16x32_bf16 v[22:25], v[178:181], v[216:219], v[22:25]
	v_mfma_f32_16x16x32_bf16 v[18:21], v[186:189], v[216:219], v[18:21]
	v_mfma_f32_16x16x32_bf16 v[6:9], v[178:181], v[224:227], v[6:9]
	v_mfma_f32_16x16x32_bf16 v[2:5], v[186:189], v[224:227], v[2:5]
	v_mfma_f32_16x16x32_bf16 v[54:57], v[182:185], v[204:207], v[54:57]
	v_mfma_f32_16x16x32_bf16 v[50:53], v[190:193], v[204:207], v[50:53]
	v_mfma_f32_16x16x32_bf16 v[38:41], v[182:185], v[212:215], v[38:41]
	v_mfma_f32_16x16x32_bf16 v[34:37], v[190:193], v[212:215], v[34:37]
	v_mfma_f32_16x16x32_bf16 v[22:25], v[182:185], v[220:223], v[22:25]
	v_mfma_f32_16x16x32_bf16 v[18:21], v[190:193], v[220:223], v[18:21]
	v_mfma_f32_16x16x32_bf16 v[6:9], v[182:185], v[228:231], v[6:9]
	v_mfma_f32_16x16x32_bf16 v[2:5], v[190:193], v[228:231], v[2:5]
	s_setprio 0
	s_barrier
	s_add_i32 s69, s69, 2
	s_add_u32 s30, s30, 0x100
	s_addc_u32 s31, s31, 0
	s_add_u32 s67, s67, 0x100
	s_addc_u32 s68, s68, 0
	s_cmp_gt_u32 s69, 29
	s_cbranch_scc0 .LBB0_139
	s_and_b64 vcc, exec, s[16:17]
	s_cbranch_vccz .LBB0_142
	s_barrier

; #define PG8_STAGE(bufoff, gbase, voff) do { _Pragma("unroll") for (int _i = 0; _i < 2; ++_i) \
;         __builtin_amdgcn_global_load_lds((const unsigned*)((const char*)(gbase) + (voff)[_i]), (PG8_LAS unsigned*)(lds + (bufoff) + ldsw + _i * 8192), 16, 0, 0); } while (0)
; #define PG8_LDA(dst, b, h) do { _Pragma("unroll") for (int m = 0; m < 4; ++m) _Pragma("unroll") for (int k = 0; k < 2; ++k) dst[m][k] = *(const PG8_LAS bf16x8*)(lds + PG8_SA(b, h) + aoff + m * 2048 + k * 1024); } while (0)
; #define PG8_LDB(dst, b, h) do { _Pragma("unroll") for (int n = 0; n < 2; ++n) _Pragma("unroll") for (int k = 0; k < 2; ++k) dst[n][k] = *(const PG8_LAS bf16x8*)(lds + PG8_SB(b, h) + boff + n * 2048 + k * 1024); } while (0)
; #define PG8_MMA(ai, bj, At, Bt) do { __builtin_amdgcn_s_setprio(1); _Pragma("unroll") for (int m = 0; m < 4; ++m) _Pragma("unroll") for (int n = 0; n < 2; ++n) _Pragma("unroll") for (int k = 0; k < 2; ++k) \
;         acc[ai][bj][m][n] = __builtin_amdgcn_mfma_f32_16x16x32_bf16(Bt[n][k], At[m][k], acc[ai][bj][m][n], 0, 0, 0); __builtin_amdgcn_s_setprio(0); } while (0)
; #define PG8_WAIT_V(n) asm volatile("s_waitcnt vmcnt(" #n ")" ::: "memory")
; #define PG8_WAIT_L(n) asm volatile("s_waitcnt lgkmcnt(" #n ")" ::: "memory")
; #define PG8_BAR __builtin_amdgcn_s_barrier()
; #define PG8_SCHED __builtin_amdgcn_sched_barrier(0)
; template <class Epi, class Sched, bool ALIGN_EPI = false, bool SP2 = false>
; __device__ __forceinline__ void gemm_phase(PG8_LAS unsigned char* lds, const Gemm g, const Sched& S, const Epi& E) {
;     ...
;             PG8_LDB(B0, 0, 0); PG8_LDB(B1, 0, 1); PG8_SCHED; PG8_LDA(At, 0, 0); PG8_STAGE(PG8_SA(1, 1), a1 + hstep, voffA);
;             PG8_WAIT_V(8); PG8_WAIT_L(0); PG8_BAR; PG8_MMA(0, 0, At, B0); PG8_MMA(0, 1, At, B1); PG8_BAR; PG8_SCHED;
;             PG8_LDA(At, 0, 1); PG8_STAGE(PG8_SB(0, 0), b2, voffB); PG8_STAGE(PG8_SB(0, 1), b2 + hstep, voffB); PG8_STAGE(PG8_SA(0, 0), a2, voffA);
;             PG8_WAIT_V(8); PG8_WAIT_L(0); PG8_BAR; PG8_MMA(1, 0, At, B0); PG8_MMA(1, 1, At, B1); PG8_BAR; PG8_SCHED;
.LBB0_667:
	s_add_u32 s30, s0, 0xfff80080
	s_addc_u32 s31, s1, -1
	s_add_i32 s66, 0, 0x10000
	s_cmp_eq_u32 s63, 28
	s_cselect_b32 s37, s23, s31
	s_cselect_b32 s36, s59, s30
	s_cselect_b32 s31, s19, s62
	s_cselect_b32 s30, s60, s61
	s_add_i32 s68, 0, 0x14000
	v_add_u32_e32 v142, s66, v199
	v_add_u32_e32 v162, s68, v199
	ds_read_b128 v[130:133], v142
	ds_read_b128 v[134:137], v142 offset:1024
	ds_read_b128 v[138:141], v142 offset:2048
	ds_read_b128 v[142:145], v142 offset:3072
	ds_read_b128 v[146:149], v162
	ds_read_b128 v[150:153], v162 offset:1024
	ds_read_b128 v[154:157], v162 offset:2048
	ds_read_b128 v[162:165], v162 offset:3072
	s_add_u32 s98, s0, 0xfff80000
	s_addc_u32 s99, s1, -1
	v_lshl_add_u64 v[192:193], s[98:99], 0, v[172:173]
	s_mov_b32 m0, s54
	s_nop 0
	global_load_lds_dwordx4 v[192:193], off
	v_lshl_add_u64 v[192:193], s[98:99], 0, v[174:175]
	s_mov_b32 m0, s55
	s_nop 0
	global_load_lds_dwordx4 v[192:193], off
	v_lshl_add_u64 v[192:193], s[0:1], 0, v[172:173]
	s_add_i32 m0, s48, 0xc000
	ds_read_b128 v[176:179], v201
	ds_read_b128 v[180:183], v201 offset:1024
	ds_read_b128 v[184:187], v201 offset:2048
	ds_read_b128 v[188:191], v201 offset:3072
	ds_read_b128 v[202:205], v201 offset:4096
	ds_read_b128 v[206:209], v201 offset:5120
	ds_read_b128 v[210:213], v201 offset:6144
	ds_read_b128 v[214:217], v201 offset:7168
	global_load_lds_dwordx4 v[192:193], off
	v_lshl_add_u64 v[192:193], s[0:1], 0, v[174:175]
	s_add_i32 m0, s48, 0xe000
	s_nop 0
	global_load_lds_dwordx4 v[192:193], off
	s_waitcnt vmcnt(8)
	s_waitcnt lgkmcnt(0)
	s_barrier
	s_setprio 1
	s_waitcnt lgkmcnt(0)
	v_mfma_f32_16x16x32_bf16 v[126:129], v[130:133], v[176:179], v[126:129]
	v_mfma_f32_16x16x32_bf16 v[122:125], v[138:141], v[176:179], v[122:125]
	v_mfma_f32_16x16x32_bf16 v[110:113], v[130:133], v[184:187], v[110:113]
	v_mfma_f32_16x16x32_bf16 v[106:109], v[138:141], v[184:187], v[106:109]
	v_mfma_f32_16x16x32_bf16 v[94:97], v[130:133], v[202:205], v[94:97]
	v_mfma_f32_16x16x32_bf16 v[90:93], v[138:141], v[202:205], v[90:93]
	v_mfma_f32_16x16x32_bf16 v[78:81], v[130:133], v[210:213], v[78:81]
	v_mfma_f32_16x16x32_bf16 v[74:77], v[138:141], v[210:213], v[74:77]
	v_mfma_f32_16x16x32_bf16 v[126:129], v[134:137], v[180:183], v[126:129]
	v_mfma_f32_16x16x32_bf16 v[122:125], v[142:145], v[180:183], v[122:125]
	v_mfma_f32_16x16x32_bf16 v[110:113], v[134:137], v[188:191], v[110:113]
	v_mfma_f32_16x16x32_bf16 v[106:109], v[142:145], v[188:191], v[106:109]
	v_mfma_f32_16x16x32_bf16 v[94:97], v[134:137], v[206:209], v[94:97]
	v_mfma_f32_16x16x32_bf16 v[90:93], v[142:145], v[206:209], v[90:93]
	v_mfma_f32_16x16x32_bf16 v[78:81], v[134:137], v[214:217], v[78:81]
	v_mfma_f32_16x16x32_bf16 v[74:77], v[142:145], v[214:217], v[74:77]
	s_setprio 0
	s_setprio 1
	v_mfma_f32_16x16x32_bf16 v[118:121], v[146:149], v[176:179], v[118:121]
	v_mfma_f32_16x16x32_bf16 v[114:117], v[154:157], v[176:179], v[114:117]
	v_mfma_f32_16x16x32_bf16 v[102:105], v[146:149], v[184:187], v[102:105]
	v_mfma_f32_16x16x32_bf16 v[98:101], v[154:157], v[184:187], v[98:101]
	v_mfma_f32_16x16x32_bf16 v[86:89], v[146:149], v[202:205], v[86:89]
	v_mfma_f32_16x16x32_bf16 v[82:85], v[154:157], v[202:205], v[82:85]
	v_mfma_f32_16x16x32_bf16 v[70:73], v[146:149], v[210:213], v[70:73]
	v_mfma_f32_16x16x32_bf16 v[66:69], v[154:157], v[210:213], v[66:69]
	v_mfma_f32_16x16x32_bf16 v[118:121], v[150:153], v[180:183], v[118:121]
	v_mfma_f32_16x16x32_bf16 v[114:117], v[162:165], v[180:183], v[114:117]
	v_mfma_f32_16x16x32_bf16 v[102:105], v[150:153], v[188:191], v[102:105]
	v_mfma_f32_16x16x32_bf16 v[98:101], v[162:165], v[188:191], v[98:101]
	v_mfma_f32_16x16x32_bf16 v[86:89], v[150:153], v[206:209], v[86:89]
	v_mfma_f32_16x16x32_bf16 v[82:85], v[162:165], v[206:209], v[82:85]
	v_mfma_f32_16x16x32_bf16 v[70:73], v[150:153], v[214:217], v[70:73]
	v_mfma_f32_16x16x32_bf16 v[66:69], v[162:165], v[214:217], v[66:69]
	s_setprio 0
	s_barrier
	s_add_i32 s66, s66, s47
	v_lshl_add_u64 v[192:193], s[30:31], 0, v[158:159]
	s_mov_b32 m0, s66
	ds_read_b128 v[176:179], v201 offset:16384
	ds_read_b128 v[180:183], v201 offset:17408
	ds_read_b128 v[184:187], v201 offset:18432
	ds_read_b128 v[188:191], v201 offset:19456
	ds_read_b128 v[202:205], v201 offset:20480
	ds_read_b128 v[206:209], v201 offset:21504
	ds_read_b128 v[210:213], v201 offset:22528
	ds_read_b128 v[214:217], v201 offset:23552
	global_load_lds_dwordx4 v[192:193], off
	s_add_i32 m0, s66, 0x2000
	s_add_u32 s66, s30, 0x80000
	v_lshl_add_u64 v[218:219], s[30:31], 0, v[166:167]
	s_addc_u32 s67, s31, 0
	s_add_i32 s68, s68, s47
	global_load_lds_dwordx4 v[218:219], off
	v_lshl_add_u64 v[220:221], s[66:67], 0, v[158:159]
	s_mov_b32 m0, s68
	v_lshl_add_u64 v[222:223], s[36:37], 0, v[168:169]
	global_load_lds_dwordx4 v[220:221], off
	v_lshl_add_u64 v[220:221], s[66:67], 0, v[166:167]
	s_add_i32 m0, s68, 0x2000
	s_nop 0
	global_load_lds_dwordx4 v[220:221], off
	v_lshl_add_u64 v[220:221], s[36:37], 0, v[170:171]
	s_waitcnt vmcnt(6)
	s_waitcnt lgkmcnt(0)
	s_barrier
; #define PG8_STAGE(bufoff, gbase, voff) do { _Pragma("unroll") for (int _i = 0; _i < 2; ++_i) \
;         __builtin_amdgcn_global_load_lds((const unsigned*)((const char*)(gbase) + (voff)[_i]), (PG8_LAS unsigned*)(lds + (bufoff) + ldsw + _i * 8192), 16, 0, 0); } while (0)
; #define PG8_LDA(dst, b, h) do { _Pragma("unroll") for (int m = 0; m < 4; ++m) _Pragma("unroll") for (int k = 0; k < 2; ++k) dst[m][k] = *(const PG8_LAS bf16x8*)(lds + PG8_SA(b, h) + aoff + m * 2048 + k * 1024); } while (0)
; #define PG8_LDB(dst, b, h) do { _Pragma("unroll") for (int n = 0; n < 2; ++n) _Pragma("unroll") for (int k = 0; k < 2; ++k) dst[n][k] = *(const PG8_LAS bf16x8*)(lds + PG8_SB(b, h) + boff + n * 2048 + k * 1024); } while (0)
; #define PG8_MMA(ai, bj, At, Bt) do { __builtin_amdgcn_s_setprio(1); _Pragma("unroll") for (int m = 0; m < 4; ++m) _Pragma("unroll") for (int n = 0; n < 2; ++n) _Pragma("unroll") for (int k = 0; k < 2; ++k) \
;         acc[ai][bj][m][n] = __builtin_amdgcn_mfma_f32_16x16x32_bf16(Bt[n][k], At[m][k], acc[ai][bj][m][n], 0, 0, 0); __builtin_amdgcn_s_setprio(0); } while (0)
; #define PG8_WAIT_V(n) asm volatile("s_waitcnt vmcnt(" #n ")" ::: "memory")
; #define PG8_WAIT_L(n) asm volatile("s_waitcnt lgkmcnt(" #n ")" ::: "memory")
; #define PG8_BAR __builtin_amdgcn_s_barrier()
; #define PG8_SCHED __builtin_amdgcn_sched_barrier(0)
; template <class Epi, class Sched, bool ALIGN_EPI = false, bool SP2 = false>
; __device__ __forceinline__ void gemm_phase(PG8_LAS unsigned char* lds, const Gemm g, const Sched& S, const Epi& E) {
;     ...
;             PG8_WAIT_V(8); PG8_WAIT_L(0); PG8_BAR; PG8_MMA(1, 0, At, B0); PG8_MMA(1, 1, At, B1); PG8_BAR; PG8_SCHED;
;             PG8_LDB(B0, 1, 0); PG8_LDB(B1, 1, 1); PG8_SCHED; PG8_LDA(At, 1, 0); PG8_STAGE(PG8_SA(0, 1), a2 + hstep, voffA);
;             PG8_WAIT_V(8); PG8_WAIT_L(0); PG8_BAR; PG8_MMA(0, 0, At, B0); PG8_MMA(0, 1, At, B1); PG8_BAR; PG8_SCHED;
	s_setprio 1
	s_waitcnt lgkmcnt(0)
	v_mfma_f32_16x16x32_bf16 v[62:65], v[130:133], v[176:179], v[62:65]
	v_mfma_f32_16x16x32_bf16 v[58:61], v[138:141], v[176:179], v[58:61]
	v_mfma_f32_16x16x32_bf16 v[46:49], v[130:133], v[184:187], v[46:49]
	v_mfma_f32_16x16x32_bf16 v[42:45], v[138:141], v[184:187], v[42:45]
	v_mfma_f32_16x16x32_bf16 v[30:33], v[130:133], v[202:205], v[30:33]
	v_mfma_f32_16x16x32_bf16 v[26:29], v[138:141], v[202:205], v[26:29]
	v_mfma_f32_16x16x32_bf16 v[14:17], v[130:133], v[210:213], v[14:17]
	v_mfma_f32_16x16x32_bf16 v[10:13], v[138:141], v[210:213], v[10:13]
	v_mfma_f32_16x16x32_bf16 v[62:65], v[134:137], v[180:183], v[62:65]
	v_mfma_f32_16x16x32_bf16 v[58:61], v[142:145], v[180:183], v[58:61]
	v_mfma_f32_16x16x32_bf16 v[46:49], v[134:137], v[188:191], v[46:49]
	v_mfma_f32_16x16x32_bf16 v[42:45], v[142:145], v[188:191], v[42:45]
	v_mfma_f32_16x16x32_bf16 v[30:33], v[134:137], v[206:209], v[30:33]
	v_mfma_f32_16x16x32_bf16 v[26:29], v[142:145], v[206:209], v[26:29]
	v_mfma_f32_16x16x32_bf16 v[14:17], v[134:137], v[214:217], v[14:17]
	v_mfma_f32_16x16x32_bf16 v[10:13], v[142:145], v[214:217], v[10:13]
	s_setprio 0
	s_setprio 1
	v_mfma_f32_16x16x32_bf16 v[54:57], v[146:149], v[176:179], v[54:57]
	v_mfma_f32_16x16x32_bf16 v[50:53], v[154:157], v[176:179], v[50:53]
	v_mfma_f32_16x16x32_bf16 v[38:41], v[146:149], v[184:187], v[38:41]
	v_mfma_f32_16x16x32_bf16 v[34:37], v[154:157], v[184:187], v[34:37]
	v_mfma_f32_16x16x32_bf16 v[22:25], v[146:149], v[202:205], v[22:25]
	v_mfma_f32_16x16x32_bf16 v[18:21], v[154:157], v[202:205], v[18:21]
	v_mfma_f32_16x16x32_bf16 v[6:9], v[146:149], v[210:213], v[6:9]
	v_mfma_f32_16x16x32_bf16 v[2:5], v[154:157], v[210:213], v[2:5]
	v_mfma_f32_16x16x32_bf16 v[54:57], v[150:153], v[180:183], v[54:57]
	v_mfma_f32_16x16x32_bf16 v[50:53], v[162:165], v[180:183], v[50:53]
	v_mfma_f32_16x16x32_bf16 v[38:41], v[150:153], v[188:191], v[38:41]
	v_mfma_f32_16x16x32_bf16 v[34:37], v[162:165], v[188:191], v[34:37]
	v_mfma_f32_16x16x32_bf16 v[22:25], v[150:153], v[206:209], v[22:25]
	v_mfma_f32_16x16x32_bf16 v[18:21], v[162:165], v[206:209], v[18:21]
	v_mfma_f32_16x16x32_bf16 v[6:9], v[150:153], v[214:217], v[6:9]
	v_mfma_f32_16x16x32_bf16 v[2:5], v[162:165], v[214:217], v[2:5]
	s_setprio 0
	s_barrier
	s_add_i32 s66, 0, 0x18000
	s_add_i32 s67, 0, 0x1c000
	v_add_u32_e32 v142, s66, v199
	v_add_u32_e32 v162, s67, v199
	ds_read_b128 v[130:133], v142
	ds_read_b128 v[134:137], v142 offset:1024
	ds_read_b128 v[138:141], v142 offset:2048
	ds_read_b128 v[142:145], v142 offset:3072
	ds_read_b128 v[146:149], v162
	ds_read_b128 v[150:153], v162 offset:1024
	ds_read_b128 v[154:157], v162 offset:2048
	ds_read_b128 v[162:165], v162 offset:3072
	s_add_u32 s36, s36, 0x80000
	s_addc_u32 s37, s37, 0
	s_mov_b32 m0, s48
	s_nop 0
	global_load_lds_dwordx4 v[220:221], off
	s_mov_b32 m0, s49
	s_nop 0
	global_load_lds_dwordx4 v[222:223], off
	s_mov_b32 m0, s50
	v_lshl_add_u64 v[224:225], s[36:37], 0, v[170:171]
	ds_read_b128 v[176:179], v201 offset:32768
	ds_read_b128 v[180:183], v201 offset:33792
	ds_read_b128 v[184:187], v201 offset:34816
	ds_read_b128 v[188:191], v201 offset:35840
	ds_read_b128 v[202:205], v201 offset:36864
	ds_read_b128 v[206:209], v201 offset:37888
	ds_read_b128 v[210:213], v201 offset:38912
	ds_read_b128 v[214:217], v201 offset:39936
	global_load_lds_dwordx4 v[224:225], off
	v_lshl_add_u64 v[224:225], s[36:37], 0, v[168:169]
	s_mov_b32 m0, s51
	s_nop 0
	global_load_lds_dwordx4 v[224:225], off
	s_waitcnt vmcnt(8)
	s_waitcnt lgkmcnt(0)
	s_barrier
; #define PG8_STAGE(bufoff, gbase, voff) do { _Pragma("unroll") for (int _i = 0; _i < 2; ++_i) \
;         __builtin_amdgcn_global_load_lds((const unsigned*)((const char*)(gbase) + (voff)[_i]), (PG8_LAS unsigned*)(lds + (bufoff) + ldsw + _i * 8192), 16, 0, 0); } while (0)
; #define PG8_LDA(dst, b, h) do { _Pragma("unroll") for (int m = 0; m < 4; ++m) _Pragma("unroll") for (int k = 0; k < 2; ++k) dst[m][k] = *(const PG8_LAS bf16x8*)(lds + PG8_SA(b, h) + aoff + m * 2048 + k * 1024); } while (0)
; #define PG8_MMA(ai, bj, At, Bt) do { __builtin_amdgcn_s_setprio(1); _Pragma("unroll") for (int m = 0; m < 4; ++m) _Pragma("unroll") for (int n = 0; n < 2; ++n) _Pragma("unroll") for (int k = 0; k < 2; ++k) \
;         acc[ai][bj][m][n] = __builtin_amdgcn_mfma_f32_16x16x32_bf16(Bt[n][k], At[m][k], acc[ai][bj][m][n], 0, 0, 0); __builtin_amdgcn_s_setprio(0); } while (0)
; #define PG8_WAIT_V(n) asm volatile("s_waitcnt vmcnt(" #n ")" ::: "memory")
; #define PG8_WAIT_L(n) asm volatile("s_waitcnt lgkmcnt(" #n ")" ::: "memory")
; #define PG8_BAR __builtin_amdgcn_s_barrier()
; #define PG8_SCHED __builtin_amdgcn_sched_barrier(0)
; template <class Epi, class Sched, bool ALIGN_EPI = false, bool SP2 = false>
; __device__ __forceinline__ void gemm_phase(PG8_LAS unsigned char* lds, const Gemm g, const Sched& S, const Epi& E) {
;     ...
;             PG8_WAIT_V(8); PG8_WAIT_L(0); PG8_BAR; PG8_MMA(0, 0, At, B0); PG8_MMA(0, 1, At, B1); PG8_BAR; PG8_SCHED;
;             PG8_LDA(At, 1, 1); PG8_STAGE(PG8_SB(1, 0), b3, voffB); PG8_STAGE(PG8_SB(1, 1), b3 + hstep, voffB); PG8_STAGE(PG8_SA(1, 0), a3, voffA);
;             PG8_WAIT_V(8); PG8_WAIT_L(0); PG8_BAR; PG8_MMA(1, 0, At, B0); PG8_MMA(1, 1, At, B1); PG8_BAR; PG8_SCHED;
	s_setprio 1
	s_waitcnt lgkmcnt(0)
	v_mfma_f32_16x16x32_bf16 v[126:129], v[130:133], v[176:179], v[126:129]
	v_mfma_f32_16x16x32_bf16 v[122:125], v[138:141], v[176:179], v[122:125]
	v_mfma_f32_16x16x32_bf16 v[110:113], v[130:133], v[184:187], v[110:113]
	v_mfma_f32_16x16x32_bf16 v[106:109], v[138:141], v[184:187], v[106:109]
	v_mfma_f32_16x16x32_bf16 v[94:97], v[130:133], v[202:205], v[94:97]
	v_mfma_f32_16x16x32_bf16 v[90:93], v[138:141], v[202:205], v[90:93]
	v_mfma_f32_16x16x32_bf16 v[78:81], v[130:133], v[210:213], v[78:81]
	v_mfma_f32_16x16x32_bf16 v[74:77], v[138:141], v[210:213], v[74:77]
	v_mfma_f32_16x16x32_bf16 v[126:129], v[134:137], v[180:183], v[126:129]
	v_mfma_f32_16x16x32_bf16 v[122:125], v[142:145], v[180:183], v[122:125]
	v_mfma_f32_16x16x32_bf16 v[110:113], v[134:137], v[188:191], v[110:113]
	v_mfma_f32_16x16x32_bf16 v[106:109], v[142:145], v[188:191], v[106:109]
	v_mfma_f32_16x16x32_bf16 v[94:97], v[134:137], v[206:209], v[94:97]
	v_mfma_f32_16x16x32_bf16 v[90:93], v[142:145], v[206:209], v[90:93]
	v_mfma_f32_16x16x32_bf16 v[78:81], v[134:137], v[214:217], v[78:81]
	v_mfma_f32_16x16x32_bf16 v[74:77], v[142:145], v[214:217], v[74:77]
	s_setprio 0
	s_setprio 1
	v_mfma_f32_16x16x32_bf16 v[118:121], v[146:149], v[176:179], v[118:121]
	v_mfma_f32_16x16x32_bf16 v[114:117], v[154:157], v[176:179], v[114:117]
	v_mfma_f32_16x16x32_bf16 v[102:105], v[146:149], v[184:187], v[102:105]
	v_mfma_f32_16x16x32_bf16 v[98:101], v[154:157], v[184:187], v[98:101]
	v_mfma_f32_16x16x32_bf16 v[86:89], v[146:149], v[202:205], v[86:89]
	v_mfma_f32_16x16x32_bf16 v[82:85], v[154:157], v[202:205], v[82:85]
	v_mfma_f32_16x16x32_bf16 v[70:73], v[146:149], v[210:213], v[70:73]
	v_mfma_f32_16x16x32_bf16 v[66:69], v[154:157], v[210:213], v[66:69]
	v_mfma_f32_16x16x32_bf16 v[118:121], v[150:153], v[180:183], v[118:121]
	v_mfma_f32_16x16x32_bf16 v[114:117], v[162:165], v[180:183], v[114:117]
	v_mfma_f32_16x16x32_bf16 v[102:105], v[150:153], v[188:191], v[102:105]
	v_mfma_f32_16x16x32_bf16 v[98:101], v[162:165], v[188:191], v[98:101]
	v_mfma_f32_16x16x32_bf16 v[86:89], v[150:153], v[206:209], v[86:89]
	v_mfma_f32_16x16x32_bf16 v[82:85], v[162:165], v[206:209], v[82:85]
	v_mfma_f32_16x16x32_bf16 v[70:73], v[150:153], v[214:217], v[70:73]
	v_mfma_f32_16x16x32_bf16 v[66:69], v[162:165], v[214:217], v[66:69]
	s_setprio 0
	s_barrier
	s_add_i32 s36, s66, s47
	v_lshl_add_u64 v[192:193], v[192:193], 0, s[10:11]
	s_mov_b32 m0, s36
	ds_read_b128 v[176:179], v201 offset:49152
	ds_read_b128 v[180:183], v201 offset:50176
	ds_read_b128 v[184:187], v201 offset:51200
	ds_read_b128 v[188:191], v201 offset:52224
	ds_read_b128 v[202:205], v201 offset:53248
	ds_read_b128 v[206:209], v201 offset:54272
	ds_read_b128 v[210:213], v201 offset:55296
	ds_read_b128 v[214:217], v201 offset:56320
	global_load_lds_dwordx4 v[192:193], off
	s_add_i32 m0, s36, 0x2000
	s_add_u32 s30, s30, 0x80080
	v_lshl_add_u64 v[192:193], v[218:219], 0, s[10:11]
	s_addc_u32 s31, s31, 0
	s_add_i32 s36, s67, s47
	global_load_lds_dwordx4 v[192:193], off
	v_lshl_add_u64 v[192:193], s[30:31], 0, v[158:159]
	s_mov_b32 m0, s36
	s_nop 0
	global_load_lds_dwordx4 v[192:193], off
	v_lshl_add_u64 v[192:193], s[30:31], 0, v[166:167]
	s_add_i32 m0, s36, 0x2000
	s_nop 0
	global_load_lds_dwordx4 v[192:193], off
	s_waitcnt vmcnt(6)
	s_waitcnt lgkmcnt(0)
	s_barrier
	s_setprio 1
	s_waitcnt lgkmcnt(0)
	v_mfma_f32_16x16x32_bf16 v[62:65], v[130:133], v[176:179], v[62:65]
	v_mfma_f32_16x16x32_bf16 v[58:61], v[138:141], v[176:179], v[58:61]
	v_mfma_f32_16x16x32_bf16 v[46:49], v[130:133], v[184:187], v[46:49]
	v_mfma_f32_16x16x32_bf16 v[42:45], v[138:141], v[184:187], v[42:45]
	v_mfma_f32_16x16x32_bf16 v[30:33], v[130:133], v[202:205], v[30:33]
	v_mfma_f32_16x16x32_bf16 v[26:29], v[138:141], v[202:205], v[26:29]
	v_mfma_f32_16x16x32_bf16 v[14:17], v[130:133], v[210:213], v[14:17]
	v_mfma_f32_16x16x32_bf16 v[10:13], v[138:141], v[210:213], v[10:13]
	v_mfma_f32_16x16x32_bf16 v[62:65], v[134:137], v[180:183], v[62:65]
	v_mfma_f32_16x16x32_bf16 v[58:61], v[142:145], v[180:183], v[58:61]
	v_mfma_f32_16x16x32_bf16 v[46:49], v[134:137], v[188:191], v[46:49]
	v_mfma_f32_16x16x32_bf16 v[42:45], v[142:145], v[188:191], v[42:45]
	v_mfma_f32_16x16x32_bf16 v[30:33], v[134:137], v[206:209], v[30:33]
	v_mfma_f32_16x16x32_bf16 v[26:29], v[142:145], v[206:209], v[26:29]
	v_mfma_f32_16x16x32_bf16 v[14:17], v[134:137], v[214:217], v[14:17]
	v_mfma_f32_16x16x32_bf16 v[10:13], v[142:145], v[214:217], v[10:13]
	s_setprio 0
	s_setprio 1
	v_mfma_f32_16x16x32_bf16 v[54:57], v[146:149], v[176:179], v[54:57]
	v_mfma_f32_16x16x32_bf16 v[50:53], v[154:157], v[176:179], v[50:53]
	v_mfma_f32_16x16x32_bf16 v[38:41], v[146:149], v[184:187], v[38:41]
	v_mfma_f32_16x16x32_bf16 v[34:37], v[154:157], v[184:187], v[34:37]
	v_mfma_f32_16x16x32_bf16 v[22:25], v[146:149], v[202:205], v[22:25]
	v_mfma_f32_16x16x32_bf16 v[18:21], v[154:157], v[202:205], v[18:21]
	v_mfma_f32_16x16x32_bf16 v[6:9], v[146:149], v[210:213], v[6:9]
	v_mfma_f32_16x16x32_bf16 v[2:5], v[154:157], v[210:213], v[2:5]
	v_mfma_f32_16x16x32_bf16 v[54:57], v[150:153], v[180:183], v[54:57]
	v_mfma_f32_16x16x32_bf16 v[50:53], v[162:165], v[180:183], v[50:53]
	v_mfma_f32_16x16x32_bf16 v[38:41], v[150:153], v[188:191], v[38:41]
	v_mfma_f32_16x16x32_bf16 v[34:37], v[162:165], v[188:191], v[34:37]
	v_mfma_f32_16x16x32_bf16 v[22:25], v[150:153], v[206:209], v[22:25]
	v_mfma_f32_16x16x32_bf16 v[18:21], v[162:165], v[206:209], v[18:21]
	v_mfma_f32_16x16x32_bf16 v[6:9], v[150:153], v[214:217], v[6:9]
	v_mfma_f32_16x16x32_bf16 v[2:5], v[162:165], v[214:217], v[2:5]
	s_setprio 0
	s_barrier
	s_add_i32 s63, s63, 2
	s_add_u32 s0, s0, 0x100
	s_addc_u32 s1, s1, 0
	s_add_u32 s61, s61, 0x100
	s_addc_u32 s62, s62, 0
	s_cmp_gt_u32 s63, 29
	s_cbranch_scc0 .LBB0_667
	s_and_b64 vcc, exec, s[16:17]
	s_cbranch_vccz .LBB0_670
	s_barrier

; #define PG8_STAGE(bufoff, gbase, voff) do { _Pragma("unroll") for (int _i = 0; _i < 2; ++_i) \
;         __builtin_amdgcn_global_load_lds((const unsigned*)((const char*)(gbase) + (voff)[_i]), (PG8_LAS unsigned*)(lds + (bufoff) + ldsw + _i * 8192), 16, 0, 0); } while (0)
; #define PG8_LDA(dst, b, h) do { _Pragma("unroll") for (int m = 0; m < 4; ++m) _Pragma("unroll") for (int k = 0; k < 2; ++k) dst[m][k] = *(const PG8_LAS bf16x8*)(lds + PG8_SA(b, h) + aoff + m * 2048 + k * 1024); } while (0)
; #define PG8_LDB(dst, b, h) do { _Pragma("unroll") for (int n = 0; n < 2; ++n) _Pragma("unroll") for (int k = 0; k < 2; ++k) dst[n][k] = *(const PG8_LAS bf16x8*)(lds + PG8_SB(b, h) + boff + n * 2048 + k * 1024); } while (0)
; #define PG8_MMA(ai, bj, At, Bt) do { __builtin_amdgcn_s_setprio(1); _Pragma("unroll") for (int m = 0; m < 4; ++m) _Pragma("unroll") for (int n = 0; n < 2; ++n) _Pragma("unroll") for (int k = 0; k < 2; ++k) \
;         acc[ai][bj][m][n] = __builtin_amdgcn_mfma_f32_16x16x32_bf16(Bt[n][k], At[m][k], acc[ai][bj][m][n], 0, 0, 0); __builtin_amdgcn_s_setprio(0); } while (0)
; #define PG8_WAIT_V(n) asm volatile("s_waitcnt vmcnt(" #n ")" ::: "memory")
; #define PG8_WAIT_L(n) asm volatile("s_waitcnt lgkmcnt(" #n ")" ::: "memory")
; #define PG8_BAR __builtin_amdgcn_s_barrier()
; #define PG8_SCHED __builtin_amdgcn_sched_barrier(0)
; template <class Epi, class Sched, bool ALIGN_EPI = false, bool SP2 = false>
; __device__ __forceinline__ void gemm_phase(PG8_LAS unsigned char* lds, const Gemm g, const Sched& S, const Epi& E) {
;     ...
;             PG8_LDB(B0, 0, 0); PG8_LDB(B1, 0, 1); PG8_SCHED; PG8_LDA(At, 0, 0); PG8_STAGE(PG8_SA(1, 1), a1 + hstep, voffA);
;             PG8_WAIT_V(8); PG8_WAIT_L(0); PG8_BAR; PG8_MMA(0, 0, At, B0); PG8_MMA(0, 1, At, B1); PG8_BAR; PG8_SCHED;
;             PG8_LDA(At, 0, 1); PG8_STAGE(PG8_SB(0, 0), b2, voffB); PG8_STAGE(PG8_SB(0, 1), b2 + hstep, voffB); PG8_STAGE(PG8_SA(0, 0), a2, voffA);
;             PG8_WAIT_V(8); PG8_WAIT_L(0); PG8_BAR; PG8_MMA(1, 0, At, B0); PG8_MMA(1, 1, At, B1); PG8_BAR; PG8_SCHED;
.LBB0_762:
	s_add_u32 s30, s0, 0xfff80080
	s_addc_u32 s31, s1, -1
	s_add_i32 s67, 0, 0x10000
	s_cmp_eq_u32 s66, 28
	s_cselect_b32 s37, s23, s31
	s_cselect_b32 s36, s60, s30
	v_add_u32_e32 v151, s67, v146
	s_cselect_b32 s31, s19, s63
	s_cselect_b32 s30, s61, s62
	s_add_i32 s70, 0, 0x14000
	ds_read_b128 v[140:143], v151
	ds_read_b128 v[152:155], v151 offset:1024
	ds_read_b128 v[162:165], v151 offset:2048
	ds_read_b128 v[166:169], v151 offset:3072
	v_add_u32_e32 v151, s70, v146
	ds_read_b128 v[170:173], v151
	ds_read_b128 v[174:177], v151 offset:1024
	ds_read_b128 v[178:181], v151 offset:2048
	ds_read_b128 v[182:185], v151 offset:3072
	s_add_u32 s98, s0, 0xfff80000
	s_addc_u32 s99, s1, -1
	v_lshl_add_u64 v[156:157], s[98:99], 0, v[136:137]
	s_mov_b32 m0, s52
	s_nop 0
	global_load_lds_dwordx4 v[156:157], off
	v_lshl_add_u64 v[156:157], s[98:99], 0, v[138:139]
	s_mov_b32 m0, s53
	s_nop 0
	global_load_lds_dwordx4 v[156:157], off
	v_lshl_add_u64 v[156:157], s[0:1], 0, v[136:137]
	s_add_i32 m0, s47, 0xc000
	ds_read_b128 v[186:189], v150
	ds_read_b128 v[190:193], v150 offset:1024
	ds_read_b128 v[200:203], v150 offset:2048
	ds_read_b128 v[204:207], v150 offset:3072
	ds_read_b128 v[208:211], v150 offset:4096
	ds_read_b128 v[212:215], v150 offset:5120
	ds_read_b128 v[216:219], v150 offset:6144
	ds_read_b128 v[220:223], v150 offset:7168
	global_load_lds_dwordx4 v[156:157], off
	v_lshl_add_u64 v[156:157], s[0:1], 0, v[138:139]
	s_add_i32 m0, s47, 0xe000
	s_nop 0
	global_load_lds_dwordx4 v[156:157], off
	s_waitcnt vmcnt(8)
	s_waitcnt lgkmcnt(0)
	s_barrier
	s_setprio 1
	s_waitcnt lgkmcnt(0)
	v_mfma_f32_16x16x32_bf16 v[126:129], v[140:143], v[186:189], v[126:129]
	v_mfma_f32_16x16x32_bf16 v[122:125], v[162:165], v[186:189], v[122:125]
	v_mfma_f32_16x16x32_bf16 v[110:113], v[140:143], v[200:203], v[110:113]
	v_mfma_f32_16x16x32_bf16 v[106:109], v[162:165], v[200:203], v[106:109]
	v_mfma_f32_16x16x32_bf16 v[94:97], v[140:143], v[208:211], v[94:97]
	v_mfma_f32_16x16x32_bf16 v[90:93], v[162:165], v[208:211], v[90:93]
	v_mfma_f32_16x16x32_bf16 v[78:81], v[140:143], v[216:219], v[78:81]
	v_mfma_f32_16x16x32_bf16 v[74:77], v[162:165], v[216:219], v[74:77]
	v_mfma_f32_16x16x32_bf16 v[126:129], v[152:155], v[190:193], v[126:129]
	v_mfma_f32_16x16x32_bf16 v[122:125], v[166:169], v[190:193], v[122:125]
	v_mfma_f32_16x16x32_bf16 v[110:113], v[152:155], v[204:207], v[110:113]
	v_mfma_f32_16x16x32_bf16 v[106:109], v[166:169], v[204:207], v[106:109]
	v_mfma_f32_16x16x32_bf16 v[94:97], v[152:155], v[212:215], v[94:97]
	v_mfma_f32_16x16x32_bf16 v[90:93], v[166:169], v[212:215], v[90:93]
	v_mfma_f32_16x16x32_bf16 v[78:81], v[152:155], v[220:223], v[78:81]
	v_mfma_f32_16x16x32_bf16 v[74:77], v[166:169], v[220:223], v[74:77]
	s_setprio 0
	s_setprio 1
	v_mfma_f32_16x16x32_bf16 v[118:121], v[170:173], v[186:189], v[118:121]
	v_mfma_f32_16x16x32_bf16 v[114:117], v[178:181], v[186:189], v[114:117]
	v_mfma_f32_16x16x32_bf16 v[102:105], v[170:173], v[200:203], v[102:105]
	v_mfma_f32_16x16x32_bf16 v[98:101], v[178:181], v[200:203], v[98:101]
	v_mfma_f32_16x16x32_bf16 v[86:89], v[170:173], v[208:211], v[86:89]
	v_mfma_f32_16x16x32_bf16 v[82:85], v[178:181], v[208:211], v[82:85]
	v_mfma_f32_16x16x32_bf16 v[70:73], v[170:173], v[216:219], v[70:73]
	v_mfma_f32_16x16x32_bf16 v[66:69], v[178:181], v[216:219], v[66:69]
	v_mfma_f32_16x16x32_bf16 v[118:121], v[174:177], v[190:193], v[118:121]
	v_mfma_f32_16x16x32_bf16 v[114:117], v[182:185], v[190:193], v[114:117]
	v_mfma_f32_16x16x32_bf16 v[102:105], v[174:177], v[204:207], v[102:105]
	v_mfma_f32_16x16x32_bf16 v[98:101], v[182:185], v[204:207], v[98:101]
	v_mfma_f32_16x16x32_bf16 v[86:89], v[174:177], v[212:215], v[86:89]
	v_mfma_f32_16x16x32_bf16 v[82:85], v[182:185], v[212:215], v[82:85]
	v_mfma_f32_16x16x32_bf16 v[70:73], v[174:177], v[220:223], v[70:73]
	v_mfma_f32_16x16x32_bf16 v[66:69], v[182:185], v[220:223], v[66:69]
	s_setprio 0
	s_barrier
	s_add_i32 s67, s67, s46
	v_lshl_add_u64 v[156:157], s[30:31], 0, v[158:159]
	s_mov_b32 m0, s67
	ds_read_b128 v[186:189], v150 offset:16384
	ds_read_b128 v[190:193], v150 offset:17408
	ds_read_b128 v[200:203], v150 offset:18432
	ds_read_b128 v[204:207], v150 offset:19456
	ds_read_b128 v[208:211], v150 offset:20480
	ds_read_b128 v[212:215], v150 offset:21504
	ds_read_b128 v[216:219], v150 offset:22528
	ds_read_b128 v[220:223], v150 offset:23552
	global_load_lds_dwordx4 v[156:157], off
	s_add_i32 m0, s67, 0x2000
	s_add_u32 s68, s30, 0x80000
	v_lshl_add_u64 v[224:225], s[30:31], 0, v[134:135]
	s_addc_u32 s69, s31, 0
	s_add_i32 s67, s70, s46
	global_load_lds_dwordx4 v[224:225], off
	v_lshl_add_u64 v[226:227], s[68:69], 0, v[158:159]
	s_mov_b32 m0, s67
	v_lshl_add_u64 v[228:229], s[36:37], 0, v[132:133]
	global_load_lds_dwordx4 v[226:227], off
	v_lshl_add_u64 v[226:227], s[68:69], 0, v[134:135]
	s_add_i32 m0, s67, 0x2000
	s_nop 0
	global_load_lds_dwordx4 v[226:227], off
	v_lshl_add_u64 v[226:227], s[36:37], 0, v[130:131]
	s_waitcnt vmcnt(6)
	s_waitcnt lgkmcnt(0)
	s_barrier
; #define PG8_STAGE(bufoff, gbase, voff) do { _Pragma("unroll") for (int _i = 0; _i < 2; ++_i) \
;         __builtin_amdgcn_global_load_lds((const unsigned*)((const char*)(gbase) + (voff)[_i]), (PG8_LAS unsigned*)(lds + (bufoff) + ldsw + _i * 8192), 16, 0, 0); } while (0)
; #define PG8_LDA(dst, b, h) do { _Pragma("unroll") for (int m = 0; m < 4; ++m) _Pragma("unroll") for (int k = 0; k < 2; ++k) dst[m][k] = *(const PG8_LAS bf16x8*)(lds + PG8_SA(b, h) + aoff + m * 2048 + k * 1024); } while (0)
; #define PG8_LDB(dst, b, h) do { _Pragma("unroll") for (int n = 0; n < 2; ++n) _Pragma("unroll") for (int k = 0; k < 2; ++k) dst[n][k] = *(const PG8_LAS bf16x8*)(lds + PG8_SB(b, h) + boff + n * 2048 + k * 1024); } while (0)
; #define PG8_MMA(ai, bj, At, Bt) do { __builtin_amdgcn_s_setprio(1); _Pragma("unroll") for (int m = 0; m < 4; ++m) _Pragma("unroll") for (int n = 0; n < 2; ++n) _Pragma("unroll") for (int k = 0; k < 2; ++k) \
;         acc[ai][bj][m][n] = __builtin_amdgcn_mfma_f32_16x16x32_bf16(Bt[n][k], At[m][k], acc[ai][bj][m][n], 0, 0, 0); __builtin_amdgcn_s_setprio(0); } while (0)
; #define PG8_WAIT_V(n) asm volatile("s_waitcnt vmcnt(" #n ")" ::: "memory")
; #define PG8_WAIT_L(n) asm volatile("s_waitcnt lgkmcnt(" #n ")" ::: "memory")
; #define PG8_BAR __builtin_amdgcn_s_barrier()
; #define PG8_SCHED __builtin_amdgcn_sched_barrier(0)
; template <class Epi, class Sched, bool ALIGN_EPI = false, bool SP2 = false>
; __device__ __forceinline__ void gemm_phase(PG8_LAS unsigned char* lds, const Gemm g, const Sched& S, const Epi& E) {
;     ...
;             PG8_WAIT_V(8); PG8_WAIT_L(0); PG8_BAR; PG8_MMA(1, 0, At, B0); PG8_MMA(1, 1, At, B1); PG8_BAR; PG8_SCHED;
;             PG8_LDB(B0, 1, 0); PG8_LDB(B1, 1, 1); PG8_SCHED; PG8_LDA(At, 1, 0); PG8_STAGE(PG8_SA(0, 1), a2 + hstep, voffA);
;             PG8_WAIT_V(8); PG8_WAIT_L(0); PG8_BAR; PG8_MMA(0, 0, At, B0); PG8_MMA(0, 1, At, B1); PG8_BAR; PG8_SCHED;
	s_setprio 1
	s_waitcnt lgkmcnt(0)
	v_mfma_f32_16x16x32_bf16 v[62:65], v[140:143], v[186:189], v[62:65]
	v_mfma_f32_16x16x32_bf16 v[58:61], v[162:165], v[186:189], v[58:61]
	v_mfma_f32_16x16x32_bf16 v[46:49], v[140:143], v[200:203], v[46:49]
	v_mfma_f32_16x16x32_bf16 v[42:45], v[162:165], v[200:203], v[42:45]
	v_mfma_f32_16x16x32_bf16 v[30:33], v[140:143], v[208:211], v[30:33]
	v_mfma_f32_16x16x32_bf16 v[26:29], v[162:165], v[208:211], v[26:29]
	v_mfma_f32_16x16x32_bf16 v[14:17], v[140:143], v[216:219], v[14:17]
	v_mfma_f32_16x16x32_bf16 v[10:13], v[162:165], v[216:219], v[10:13]
	v_mfma_f32_16x16x32_bf16 v[62:65], v[152:155], v[190:193], v[62:65]
	v_mfma_f32_16x16x32_bf16 v[58:61], v[166:169], v[190:193], v[58:61]
	v_mfma_f32_16x16x32_bf16 v[46:49], v[152:155], v[204:207], v[46:49]
	v_mfma_f32_16x16x32_bf16 v[42:45], v[166:169], v[204:207], v[42:45]
	v_mfma_f32_16x16x32_bf16 v[30:33], v[152:155], v[212:215], v[30:33]
	v_mfma_f32_16x16x32_bf16 v[26:29], v[166:169], v[212:215], v[26:29]
	v_mfma_f32_16x16x32_bf16 v[14:17], v[152:155], v[220:223], v[14:17]
	v_mfma_f32_16x16x32_bf16 v[10:13], v[166:169], v[220:223], v[10:13]
	s_setprio 0
	s_setprio 1
	v_mfma_f32_16x16x32_bf16 v[54:57], v[170:173], v[186:189], v[54:57]
	v_mfma_f32_16x16x32_bf16 v[50:53], v[178:181], v[186:189], v[50:53]
	v_mfma_f32_16x16x32_bf16 v[38:41], v[170:173], v[200:203], v[38:41]
	v_mfma_f32_16x16x32_bf16 v[34:37], v[178:181], v[200:203], v[34:37]
	v_mfma_f32_16x16x32_bf16 v[22:25], v[170:173], v[208:211], v[22:25]
	v_mfma_f32_16x16x32_bf16 v[18:21], v[178:181], v[208:211], v[18:21]
	v_mfma_f32_16x16x32_bf16 v[6:9], v[170:173], v[216:219], v[6:9]
	v_mfma_f32_16x16x32_bf16 v[2:5], v[178:181], v[216:219], v[2:5]
	v_mfma_f32_16x16x32_bf16 v[54:57], v[174:177], v[190:193], v[54:57]
	v_mfma_f32_16x16x32_bf16 v[50:53], v[182:185], v[190:193], v[50:53]
	v_mfma_f32_16x16x32_bf16 v[38:41], v[174:177], v[204:207], v[38:41]
	v_mfma_f32_16x16x32_bf16 v[34:37], v[182:185], v[204:207], v[34:37]
	v_mfma_f32_16x16x32_bf16 v[22:25], v[174:177], v[212:215], v[22:25]
	v_mfma_f32_16x16x32_bf16 v[18:21], v[182:185], v[212:215], v[18:21]
	v_mfma_f32_16x16x32_bf16 v[6:9], v[174:177], v[220:223], v[6:9]
	v_mfma_f32_16x16x32_bf16 v[2:5], v[182:185], v[220:223], v[2:5]
	s_setprio 0
	s_barrier
	s_add_i32 s67, 0, 0x18000
	v_add_u32_e32 v151, s67, v146
	s_add_i32 s68, 0, 0x1c000
	ds_read_b128 v[140:143], v151
	ds_read_b128 v[152:155], v151 offset:1024
	ds_read_b128 v[162:165], v151 offset:2048
	ds_read_b128 v[166:169], v151 offset:3072
	v_add_u32_e32 v151, s68, v146
	ds_read_b128 v[170:173], v151
	ds_read_b128 v[174:177], v151 offset:1024
	ds_read_b128 v[178:181], v151 offset:2048
	ds_read_b128 v[182:185], v151 offset:3072
	s_add_u32 s36, s36, 0x80000
	s_addc_u32 s37, s37, 0
	s_mov_b32 m0, s47
	s_nop 0
	global_load_lds_dwordx4 v[226:227], off
	s_mov_b32 m0, s48
	s_nop 0
	global_load_lds_dwordx4 v[228:229], off
	s_mov_b32 m0, s49
	v_lshl_add_u64 v[230:231], s[36:37], 0, v[130:131]
	ds_read_b128 v[186:189], v150 offset:32768
	ds_read_b128 v[190:193], v150 offset:33792
	ds_read_b128 v[200:203], v150 offset:34816
	ds_read_b128 v[204:207], v150 offset:35840
	ds_read_b128 v[208:211], v150 offset:36864
	ds_read_b128 v[212:215], v150 offset:37888
	ds_read_b128 v[216:219], v150 offset:38912
	ds_read_b128 v[220:223], v150 offset:39936
	global_load_lds_dwordx4 v[230:231], off
	v_lshl_add_u64 v[230:231], s[36:37], 0, v[132:133]
	s_mov_b32 m0, s50
	s_nop 0
	global_load_lds_dwordx4 v[230:231], off
	s_waitcnt vmcnt(8)
	s_waitcnt lgkmcnt(0)
	s_barrier
	s_setprio 1
	s_waitcnt lgkmcnt(0)
	v_mfma_f32_16x16x32_bf16 v[126:129], v[140:143], v[186:189], v[126:129]
	v_mfma_f32_16x16x32_bf16 v[122:125], v[162:165], v[186:189], v[122:125]
	v_mfma_f32_16x16x32_bf16 v[110:113], v[140:143], v[200:203], v[110:113]
	v_mfma_f32_16x16x32_bf16 v[106:109], v[162:165], v[200:203], v[106:109]
	v_mfma_f32_16x16x32_bf16 v[94:97], v[140:143], v[208:211], v[94:97]
	v_mfma_f32_16x16x32_bf16 v[90:93], v[162:165], v[208:211], v[90:93]
	v_mfma_f32_16x16x32_bf16 v[78:81], v[140:143], v[216:219], v[78:81]
	v_mfma_f32_16x16x32_bf16 v[74:77], v[162:165], v[216:219], v[74:77]
	v_mfma_f32_16x16x32_bf16 v[126:129], v[152:155], v[190:193], v[126:129]
	v_mfma_f32_16x16x32_bf16 v[122:125], v[166:169], v[190:193], v[122:125]
	v_mfma_f32_16x16x32_bf16 v[110:113], v[152:155], v[204:207], v[110:113]
	v_mfma_f32_16x16x32_bf16 v[106:109], v[166:169], v[204:207], v[106:109]
	v_mfma_f32_16x16x32_bf16 v[94:97], v[152:155], v[212:215], v[94:97]
	v_mfma_f32_16x16x32_bf16 v[90:93], v[166:169], v[212:215], v[90:93]
	v_mfma_f32_16x16x32_bf16 v[78:81], v[152:155], v[220:223], v[78:81]
	v_mfma_f32_16x16x32_bf16 v[74:77], v[166:169], v[220:223], v[74:77]
	s_setprio 0
	s_setprio 1
	v_mfma_f32_16x16x32_bf16 v[118:121], v[170:173], v[186:189], v[118:121]
	v_mfma_f32_16x16x32_bf16 v[114:117], v[178:181], v[186:189], v[114:117]
	v_mfma_f32_16x16x32_bf16 v[102:105], v[170:173], v[200:203], v[102:105]
	v_mfma_f32_16x16x32_bf16 v[98:101], v[178:181], v[200:203], v[98:101]
	v_mfma_f32_16x16x32_bf16 v[86:89], v[170:173], v[208:211], v[86:89]
	v_mfma_f32_16x16x32_bf16 v[82:85], v[178:181], v[208:211], v[82:85]
	v_mfma_f32_16x16x32_bf16 v[70:73], v[170:173], v[216:219], v[70:73]
	v_mfma_f32_16x16x32_bf16 v[66:69], v[178:181], v[216:219], v[66:69]
	v_mfma_f32_16x16x32_bf16 v[118:121], v[174:177], v[190:193], v[118:121]
	v_mfma_f32_16x16x32_bf16 v[114:117], v[182:185], v[190:193], v[114:117]
	v_mfma_f32_16x16x32_bf16 v[102:105], v[174:177], v[204:207], v[102:105]
	v_mfma_f32_16x16x32_bf16 v[98:101], v[182:185], v[204:207], v[98:101]
	v_mfma_f32_16x16x32_bf16 v[86:89], v[174:177], v[212:215], v[86:89]
	v_mfma_f32_16x16x32_bf16 v[82:85], v[182:185], v[212:215], v[82:85]
	v_mfma_f32_16x16x32_bf16 v[70:73], v[174:177], v[220:223], v[70:73]
	v_mfma_f32_16x16x32_bf16 v[66:69], v[182:185], v[220:223], v[66:69]
	s_setprio 0
	s_barrier
; #define PG8_STAGE(bufoff, gbase, voff) do { _Pragma("unroll") for (int _i = 0; _i < 2; ++_i) \
;         __builtin_amdgcn_global_load_lds((const unsigned*)((const char*)(gbase) + (voff)[_i]), (PG8_LAS unsigned*)(lds + (bufoff) + ldsw + _i * 8192), 16, 0, 0); } while (0)
; #define PG8_LDA(dst, b, h) do { _Pragma("unroll") for (int m = 0; m < 4; ++m) _Pragma("unroll") for (int k = 0; k < 2; ++k) dst[m][k] = *(const PG8_LAS bf16x8*)(lds + PG8_SA(b, h) + aoff + m * 2048 + k * 1024); } while (0)
; #define PG8_MMA(ai, bj, At, Bt) do { __builtin_amdgcn_s_setprio(1); _Pragma("unroll") for (int m = 0; m < 4; ++m) _Pragma("unroll") for (int n = 0; n < 2; ++n) _Pragma("unroll") for (int k = 0; k < 2; ++k) \
;         acc[ai][bj][m][n] = __builtin_amdgcn_mfma_f32_16x16x32_bf16(Bt[n][k], At[m][k], acc[ai][bj][m][n], 0, 0, 0); __builtin_amdgcn_s_setprio(0); } while (0)
; #define PG8_WAIT_V(n) asm volatile("s_waitcnt vmcnt(" #n ")" ::: "memory")
; #define PG8_WAIT_L(n) asm volatile("s_waitcnt lgkmcnt(" #n ")" ::: "memory")
; #define PG8_BAR __builtin_amdgcn_s_barrier()
; #define PG8_SCHED __builtin_amdgcn_sched_barrier(0)
; template <class Epi, class Sched, bool ALIGN_EPI = false, bool SP2 = false>
; __device__ __forceinline__ void gemm_phase(PG8_LAS unsigned char* lds, const Gemm g, const Sched& S, const Epi& E) {
;     ...
;             PG8_LDA(At, 1, 1); PG8_STAGE(PG8_SB(1, 0), b3, voffB); PG8_STAGE(PG8_SB(1, 1), b3 + hstep, voffB); PG8_STAGE(PG8_SA(1, 0), a3, voffA);
;             PG8_WAIT_V(8); PG8_WAIT_L(0); PG8_BAR; PG8_MMA(1, 0, At, B0); PG8_MMA(1, 1, At, B1); PG8_BAR; PG8_SCHED;
	s_add_i32 s36, s67, s46
	v_lshl_add_u64 v[156:157], v[156:157], 0, s[10:11]
	s_mov_b32 m0, s36
	ds_read_b128 v[186:189], v150 offset:49152
	ds_read_b128 v[190:193], v150 offset:50176
	ds_read_b128 v[200:203], v150 offset:51200
	ds_read_b128 v[204:207], v150 offset:52224
	ds_read_b128 v[208:211], v150 offset:53248
	ds_read_b128 v[212:215], v150 offset:54272
	ds_read_b128 v[216:219], v150 offset:55296
	ds_read_b128 v[220:223], v150 offset:56320
	global_load_lds_dwordx4 v[156:157], off
	s_add_i32 m0, s36, 0x2000
	s_add_u32 s30, s30, 0x80080
	v_lshl_add_u64 v[156:157], v[224:225], 0, s[10:11]
	s_addc_u32 s31, s31, 0
	s_add_i32 s36, s68, s46
	global_load_lds_dwordx4 v[156:157], off
	v_lshl_add_u64 v[156:157], s[30:31], 0, v[158:159]
	s_mov_b32 m0, s36
	s_nop 0
	global_load_lds_dwordx4 v[156:157], off
	v_lshl_add_u64 v[156:157], s[30:31], 0, v[134:135]
	s_add_i32 m0, s36, 0x2000
	s_nop 0
	global_load_lds_dwordx4 v[156:157], off
	s_waitcnt vmcnt(6)
	s_waitcnt lgkmcnt(0)
	s_barrier
	s_setprio 1
	s_waitcnt lgkmcnt(0)
	v_mfma_f32_16x16x32_bf16 v[62:65], v[140:143], v[186:189], v[62:65]
	v_mfma_f32_16x16x32_bf16 v[58:61], v[162:165], v[186:189], v[58:61]
	v_mfma_f32_16x16x32_bf16 v[46:49], v[140:143], v[200:203], v[46:49]
	v_mfma_f32_16x16x32_bf16 v[42:45], v[162:165], v[200:203], v[42:45]
	v_mfma_f32_16x16x32_bf16 v[30:33], v[140:143], v[208:211], v[30:33]
	v_mfma_f32_16x16x32_bf16 v[26:29], v[162:165], v[208:211], v[26:29]
	v_mfma_f32_16x16x32_bf16 v[14:17], v[140:143], v[216:219], v[14:17]
	v_mfma_f32_16x16x32_bf16 v[10:13], v[162:165], v[216:219], v[10:13]
	v_mfma_f32_16x16x32_bf16 v[62:65], v[152:155], v[190:193], v[62:65]
	v_mfma_f32_16x16x32_bf16 v[58:61], v[166:169], v[190:193], v[58:61]
	v_mfma_f32_16x16x32_bf16 v[46:49], v[152:155], v[204:207], v[46:49]
	v_mfma_f32_16x16x32_bf16 v[42:45], v[166:169], v[204:207], v[42:45]
	v_mfma_f32_16x16x32_bf16 v[30:33], v[152:155], v[212:215], v[30:33]
	v_mfma_f32_16x16x32_bf16 v[26:29], v[166:169], v[212:215], v[26:29]
	v_mfma_f32_16x16x32_bf16 v[14:17], v[152:155], v[220:223], v[14:17]
	v_mfma_f32_16x16x32_bf16 v[10:13], v[166:169], v[220:223], v[10:13]
	s_setprio 0
	s_setprio 1
	v_mfma_f32_16x16x32_bf16 v[54:57], v[170:173], v[186:189], v[54:57]
	v_mfma_f32_16x16x32_bf16 v[50:53], v[178:181], v[186:189], v[50:53]
	v_mfma_f32_16x16x32_bf16 v[38:41], v[170:173], v[200:203], v[38:41]
	v_mfma_f32_16x16x32_bf16 v[34:37], v[178:181], v[200:203], v[34:37]
	v_mfma_f32_16x16x32_bf16 v[22:25], v[170:173], v[208:211], v[22:25]
	v_mfma_f32_16x16x32_bf16 v[18:21], v[178:181], v[208:211], v[18:21]
	v_mfma_f32_16x16x32_bf16 v[6:9], v[170:173], v[216:219], v[6:9]
	v_mfma_f32_16x16x32_bf16 v[2:5], v[178:181], v[216:219], v[2:5]
	v_mfma_f32_16x16x32_bf16 v[54:57], v[174:177], v[190:193], v[54:57]
	v_mfma_f32_16x16x32_bf16 v[50:53], v[182:185], v[190:193], v[50:53]
	v_mfma_f32_16x16x32_bf16 v[38:41], v[174:177], v[204:207], v[38:41]
	v_mfma_f32_16x16x32_bf16 v[34:37], v[182:185], v[204:207], v[34:37]
	v_mfma_f32_16x16x32_bf16 v[22:25], v[174:177], v[212:215], v[22:25]
	v_mfma_f32_16x16x32_bf16 v[18:21], v[182:185], v[212:215], v[18:21]
	v_mfma_f32_16x16x32_bf16 v[6:9], v[174:177], v[220:223], v[6:9]
	v_mfma_f32_16x16x32_bf16 v[2:5], v[182:185], v[220:223], v[2:5]
	s_setprio 0
	s_barrier
	s_add_i32 s66, s66, 2
	s_add_u32 s0, s0, 0x100
	s_addc_u32 s1, s1, 0
	s_add_u32 s62, s62, 0x100
	s_addc_u32 s63, s63, 0
	s_cmp_gt_u32 s66, 29
	s_cbranch_scc0 .LBB0_762
	s_and_b64 vcc, exec, s[16:17]
	s_mov_b64 s[60:61], s[90:91]
	s_mov_b64 s[62:63], s[88:89]
	s_cbranch_vccz .LBB0_765
	s_barrier

; #define PG8_STAGE(bufoff, gbase, voff) do { _Pragma("unroll") for (int _i = 0; _i < 2; ++_i) \
;         __builtin_amdgcn_global_load_lds((const unsigned*)((const char*)(gbase) + (voff)[_i]), (PG8_LAS unsigned*)(lds + (bufoff) + ldsw + _i * 8192), 16, 0, 0); } while (0)
; #define PG8_LDA(dst, b, h) do { _Pragma("unroll") for (int m = 0; m < 4; ++m) _Pragma("unroll") for (int k = 0; k < 2; ++k) dst[m][k] = *(const PG8_LAS bf16x8*)(lds + PG8_SA(b, h) + aoff + m * 2048 + k * 1024); } while (0)
; #define PG8_LDB(dst, b, h) do { _Pragma("unroll") for (int n = 0; n < 2; ++n) _Pragma("unroll") for (int k = 0; k < 2; ++k) dst[n][k] = *(const PG8_LAS bf16x8*)(lds + PG8_SB(b, h) + boff + n * 2048 + k * 1024); } while (0)
; #define PG8_MMA(ai, bj, At, Bt) do { __builtin_amdgcn_s_setprio(1); _Pragma("unroll") for (int m = 0; m < 4; ++m) _Pragma("unroll") for (int n = 0; n < 2; ++n) _Pragma("unroll") for (int k = 0; k < 2; ++k) \
;         acc[ai][bj][m][n] = __builtin_amdgcn_mfma_f32_16x16x32_bf16(Bt[n][k], At[m][k], acc[ai][bj][m][n], 0, 0, 0); __builtin_amdgcn_s_setprio(0); } while (0)
; #define PG8_WAIT_V(n) asm volatile("s_waitcnt vmcnt(" #n ")" ::: "memory")
; #define PG8_WAIT_L(n) asm volatile("s_waitcnt lgkmcnt(" #n ")" ::: "memory")
; #define PG8_BAR __builtin_amdgcn_s_barrier()
; #define PG8_SCHED __builtin_amdgcn_sched_barrier(0)
; template <class Epi, class Sched, bool ALIGN_EPI = false, bool SP2 = false>
; __device__ __forceinline__ void gemm_phase(PG8_LAS unsigned char* lds, const Gemm g, const Sched& S, const Epi& E) {
;     ...
;             PG8_LDB(B0, 0, 0); PG8_LDB(B1, 0, 1); PG8_SCHED; PG8_LDA(At, 0, 0); PG8_STAGE(PG8_SA(1, 1), a1 + hstep, voffA);
;             PG8_WAIT_V(8); PG8_WAIT_L(0); PG8_BAR; PG8_MMA(0, 0, At, B0); PG8_MMA(0, 1, At, B1); PG8_BAR; PG8_SCHED;
;             PG8_LDA(At, 0, 1); PG8_STAGE(PG8_SB(0, 0), b2, voffB); PG8_STAGE(PG8_SB(0, 1), b2 + hstep, voffB); PG8_STAGE(PG8_SA(0, 0), a2, voffA);
;             PG8_WAIT_V(8); PG8_WAIT_L(0); PG8_BAR; PG8_MMA(1, 0, At, B0); PG8_MMA(1, 1, At, B1); PG8_BAR; PG8_SCHED;
.LBB0_842:
	s_add_u32 s30, s0, 0xffe00080
	s_addc_u32 s31, s1, -1
	s_add_i32 s68, 0, 0x10000
	s_cmpk_eq_i32 s67, 0x7c
	s_cselect_b32 s37, s23, s31
	s_cselect_b32 s36, s61, s30
	s_cselect_b32 s31, s19, s66
	s_cselect_b32 s30, s62, s63
	s_add_i32 s70, 0, 0x14000
	v_add_u32_e32 v142, s68, v199
	v_add_u32_e32 v162, s70, v199
	ds_read_b128 v[130:133], v142
	ds_read_b128 v[134:137], v142 offset:1024
	ds_read_b128 v[138:141], v142 offset:2048
	ds_read_b128 v[142:145], v142 offset:3072
	ds_read_b128 v[146:149], v162
	ds_read_b128 v[150:153], v162 offset:1024
	ds_read_b128 v[154:157], v162 offset:2048
	ds_read_b128 v[162:165], v162 offset:3072
	s_add_u32 s98, s0, 0xffe00000
	s_addc_u32 s99, s1, -1
	v_lshl_add_u64 v[192:193], s[98:99], 0, v[172:173]
	s_mov_b32 m0, s56
	s_nop 0
	global_load_lds_dwordx4 v[192:193], off
	v_lshl_add_u64 v[192:193], s[98:99], 0, v[174:175]
	s_mov_b32 m0, s57
	s_nop 0
	global_load_lds_dwordx4 v[192:193], off
	v_lshl_add_u64 v[192:193], s[0:1], 0, v[172:173]
	s_add_i32 m0, s51, 0xc000
	ds_read_b128 v[176:179], v201
	ds_read_b128 v[180:183], v201 offset:1024
	ds_read_b128 v[184:187], v201 offset:2048
	ds_read_b128 v[188:191], v201 offset:3072
	ds_read_b128 v[202:205], v201 offset:4096
	ds_read_b128 v[206:209], v201 offset:5120
	ds_read_b128 v[210:213], v201 offset:6144
	ds_read_b128 v[214:217], v201 offset:7168
	global_load_lds_dwordx4 v[192:193], off
	v_lshl_add_u64 v[192:193], s[0:1], 0, v[174:175]
	s_add_i32 m0, s51, 0xe000
	s_nop 0
	global_load_lds_dwordx4 v[192:193], off
	s_waitcnt vmcnt(8)
	s_waitcnt lgkmcnt(0)
	s_barrier
	s_setprio 1
	s_waitcnt lgkmcnt(0)
	v_mfma_f32_16x16x32_bf16 v[126:129], v[130:133], v[176:179], v[126:129]
	v_mfma_f32_16x16x32_bf16 v[122:125], v[138:141], v[176:179], v[122:125]
	v_mfma_f32_16x16x32_bf16 v[110:113], v[130:133], v[184:187], v[110:113]
	v_mfma_f32_16x16x32_bf16 v[106:109], v[138:141], v[184:187], v[106:109]
	v_mfma_f32_16x16x32_bf16 v[94:97], v[130:133], v[202:205], v[94:97]
	v_mfma_f32_16x16x32_bf16 v[90:93], v[138:141], v[202:205], v[90:93]
	v_mfma_f32_16x16x32_bf16 v[78:81], v[130:133], v[210:213], v[78:81]
	v_mfma_f32_16x16x32_bf16 v[74:77], v[138:141], v[210:213], v[74:77]
	v_mfma_f32_16x16x32_bf16 v[126:129], v[134:137], v[180:183], v[126:129]
	v_mfma_f32_16x16x32_bf16 v[122:125], v[142:145], v[180:183], v[122:125]
	v_mfma_f32_16x16x32_bf16 v[110:113], v[134:137], v[188:191], v[110:113]
	v_mfma_f32_16x16x32_bf16 v[106:109], v[142:145], v[188:191], v[106:109]
	v_mfma_f32_16x16x32_bf16 v[94:97], v[134:137], v[206:209], v[94:97]
	v_mfma_f32_16x16x32_bf16 v[90:93], v[142:145], v[206:209], v[90:93]
	v_mfma_f32_16x16x32_bf16 v[78:81], v[134:137], v[214:217], v[78:81]
	v_mfma_f32_16x16x32_bf16 v[74:77], v[142:145], v[214:217], v[74:77]
	s_setprio 0
	s_setprio 1
	v_mfma_f32_16x16x32_bf16 v[118:121], v[146:149], v[176:179], v[118:121]
	v_mfma_f32_16x16x32_bf16 v[114:117], v[154:157], v[176:179], v[114:117]
	v_mfma_f32_16x16x32_bf16 v[102:105], v[146:149], v[184:187], v[102:105]
	v_mfma_f32_16x16x32_bf16 v[98:101], v[154:157], v[184:187], v[98:101]
	v_mfma_f32_16x16x32_bf16 v[86:89], v[146:149], v[202:205], v[86:89]
	v_mfma_f32_16x16x32_bf16 v[82:85], v[154:157], v[202:205], v[82:85]
	v_mfma_f32_16x16x32_bf16 v[70:73], v[146:149], v[210:213], v[70:73]
	v_mfma_f32_16x16x32_bf16 v[66:69], v[154:157], v[210:213], v[66:69]
	v_mfma_f32_16x16x32_bf16 v[118:121], v[150:153], v[180:183], v[118:121]
	v_mfma_f32_16x16x32_bf16 v[114:117], v[162:165], v[180:183], v[114:117]
	v_mfma_f32_16x16x32_bf16 v[102:105], v[150:153], v[188:191], v[102:105]
	v_mfma_f32_16x16x32_bf16 v[98:101], v[162:165], v[188:191], v[98:101]
	v_mfma_f32_16x16x32_bf16 v[86:89], v[150:153], v[206:209], v[86:89]
	v_mfma_f32_16x16x32_bf16 v[82:85], v[162:165], v[206:209], v[82:85]
	v_mfma_f32_16x16x32_bf16 v[70:73], v[150:153], v[214:217], v[70:73]
	v_mfma_f32_16x16x32_bf16 v[66:69], v[162:165], v[214:217], v[66:69]
	s_setprio 0
	s_barrier
	s_add_i32 s68, s68, s50
	v_lshl_add_u64 v[192:193], s[30:31], 0, v[158:159]
	s_mov_b32 m0, s68
	ds_read_b128 v[176:179], v201 offset:16384
	ds_read_b128 v[180:183], v201 offset:17408
	ds_read_b128 v[184:187], v201 offset:18432
	ds_read_b128 v[188:191], v201 offset:19456
	ds_read_b128 v[202:205], v201 offset:20480
	ds_read_b128 v[206:209], v201 offset:21504
	ds_read_b128 v[210:213], v201 offset:22528
	ds_read_b128 v[214:217], v201 offset:23552
	global_load_lds_dwordx4 v[192:193], off
	s_add_i32 m0, s68, 0x2000
	s_add_u32 s68, s30, 0x200000
	v_lshl_add_u64 v[218:219], s[30:31], 0, v[166:167]
	s_addc_u32 s69, s31, 0
	s_add_i32 s70, s70, s50
	global_load_lds_dwordx4 v[218:219], off
	v_lshl_add_u64 v[220:221], s[68:69], 0, v[158:159]
	s_mov_b32 m0, s70
	v_lshl_add_u64 v[222:223], s[36:37], 0, v[168:169]
	global_load_lds_dwordx4 v[220:221], off
	v_lshl_add_u64 v[220:221], s[68:69], 0, v[166:167]
	s_add_i32 m0, s70, 0x2000
	s_nop 0
	global_load_lds_dwordx4 v[220:221], off
	v_lshl_add_u64 v[220:221], s[36:37], 0, v[170:171]
	s_waitcnt vmcnt(6)
	s_waitcnt lgkmcnt(0)
	s_barrier
; #define PG8_STAGE(bufoff, gbase, voff) do { _Pragma("unroll") for (int _i = 0; _i < 2; ++_i) \
;         __builtin_amdgcn_global_load_lds((const unsigned*)((const char*)(gbase) + (voff)[_i]), (PG8_LAS unsigned*)(lds + (bufoff) + ldsw + _i * 8192), 16, 0, 0); } while (0)
; #define PG8_LDA(dst, b, h) do { _Pragma("unroll") for (int m = 0; m < 4; ++m) _Pragma("unroll") for (int k = 0; k < 2; ++k) dst[m][k] = *(const PG8_LAS bf16x8*)(lds + PG8_SA(b, h) + aoff + m * 2048 + k * 1024); } while (0)
; #define PG8_LDB(dst, b, h) do { _Pragma("unroll") for (int n = 0; n < 2; ++n) _Pragma("unroll") for (int k = 0; k < 2; ++k) dst[n][k] = *(const PG8_LAS bf16x8*)(lds + PG8_SB(b, h) + boff + n * 2048 + k * 1024); } while (0)
; #define PG8_MMA(ai, bj, At, Bt) do { __builtin_amdgcn_s_setprio(1); _Pragma("unroll") for (int m = 0; m < 4; ++m) _Pragma("unroll") for (int n = 0; n < 2; ++n) _Pragma("unroll") for (int k = 0; k < 2; ++k) \
;         acc[ai][bj][m][n] = __builtin_amdgcn_mfma_f32_16x16x32_bf16(Bt[n][k], At[m][k], acc[ai][bj][m][n], 0, 0, 0); __builtin_amdgcn_s_setprio(0); } while (0)
; #define PG8_WAIT_V(n) asm volatile("s_waitcnt vmcnt(" #n ")" ::: "memory")
; #define PG8_WAIT_L(n) asm volatile("s_waitcnt lgkmcnt(" #n ")" ::: "memory")
; #define PG8_BAR __builtin_amdgcn_s_barrier()
; #define PG8_SCHED __builtin_amdgcn_sched_barrier(0)
; template <class Epi, class Sched, bool ALIGN_EPI = false, bool SP2 = false>
; __device__ __forceinline__ void gemm_phase(PG8_LAS unsigned char* lds, const Gemm g, const Sched& S, const Epi& E) {
;     ...
;             PG8_WAIT_V(8); PG8_WAIT_L(0); PG8_BAR; PG8_MMA(1, 0, At, B0); PG8_MMA(1, 1, At, B1); PG8_BAR; PG8_SCHED;
;             PG8_LDB(B0, 1, 0); PG8_LDB(B1, 1, 1); PG8_SCHED; PG8_LDA(At, 1, 0); PG8_STAGE(PG8_SA(0, 1), a2 + hstep, voffA);
;             PG8_WAIT_V(8); PG8_WAIT_L(0); PG8_BAR; PG8_MMA(0, 0, At, B0); PG8_MMA(0, 1, At, B1); PG8_BAR; PG8_SCHED;
	s_setprio 1
	s_waitcnt lgkmcnt(0)
	v_mfma_f32_16x16x32_bf16 v[62:65], v[130:133], v[176:179], v[62:65]
	v_mfma_f32_16x16x32_bf16 v[58:61], v[138:141], v[176:179], v[58:61]
	v_mfma_f32_16x16x32_bf16 v[46:49], v[130:133], v[184:187], v[46:49]
	v_mfma_f32_16x16x32_bf16 v[42:45], v[138:141], v[184:187], v[42:45]
	v_mfma_f32_16x16x32_bf16 v[30:33], v[130:133], v[202:205], v[30:33]
	v_mfma_f32_16x16x32_bf16 v[26:29], v[138:141], v[202:205], v[26:29]
	v_mfma_f32_16x16x32_bf16 v[14:17], v[130:133], v[210:213], v[14:17]
	v_mfma_f32_16x16x32_bf16 v[10:13], v[138:141], v[210:213], v[10:13]
	v_mfma_f32_16x16x32_bf16 v[62:65], v[134:137], v[180:183], v[62:65]
	v_mfma_f32_16x16x32_bf16 v[58:61], v[142:145], v[180:183], v[58:61]
	v_mfma_f32_16x16x32_bf16 v[46:49], v[134:137], v[188:191], v[46:49]
	v_mfma_f32_16x16x32_bf16 v[42:45], v[142:145], v[188:191], v[42:45]
	v_mfma_f32_16x16x32_bf16 v[30:33], v[134:137], v[206:209], v[30:33]
	v_mfma_f32_16x16x32_bf16 v[26:29], v[142:145], v[206:209], v[26:29]
	v_mfma_f32_16x16x32_bf16 v[14:17], v[134:137], v[214:217], v[14:17]
	v_mfma_f32_16x16x32_bf16 v[10:13], v[142:145], v[214:217], v[10:13]
	s_setprio 0
	s_setprio 1
	v_mfma_f32_16x16x32_bf16 v[54:57], v[146:149], v[176:179], v[54:57]
	v_mfma_f32_16x16x32_bf16 v[50:53], v[154:157], v[176:179], v[50:53]
	v_mfma_f32_16x16x32_bf16 v[38:41], v[146:149], v[184:187], v[38:41]
	v_mfma_f32_16x16x32_bf16 v[34:37], v[154:157], v[184:187], v[34:37]
	v_mfma_f32_16x16x32_bf16 v[22:25], v[146:149], v[202:205], v[22:25]
	v_mfma_f32_16x16x32_bf16 v[18:21], v[154:157], v[202:205], v[18:21]
	v_mfma_f32_16x16x32_bf16 v[6:9], v[146:149], v[210:213], v[6:9]
	v_mfma_f32_16x16x32_bf16 v[2:5], v[154:157], v[210:213], v[2:5]
	v_mfma_f32_16x16x32_bf16 v[54:57], v[150:153], v[180:183], v[54:57]
	v_mfma_f32_16x16x32_bf16 v[50:53], v[162:165], v[180:183], v[50:53]
	v_mfma_f32_16x16x32_bf16 v[38:41], v[150:153], v[188:191], v[38:41]
	v_mfma_f32_16x16x32_bf16 v[34:37], v[162:165], v[188:191], v[34:37]
	v_mfma_f32_16x16x32_bf16 v[22:25], v[150:153], v[206:209], v[22:25]
	v_mfma_f32_16x16x32_bf16 v[18:21], v[162:165], v[206:209], v[18:21]
	v_mfma_f32_16x16x32_bf16 v[6:9], v[150:153], v[214:217], v[6:9]
	v_mfma_f32_16x16x32_bf16 v[2:5], v[162:165], v[214:217], v[2:5]
	s_setprio 0
	s_barrier
	s_add_i32 s68, 0, 0x18000
	s_add_i32 s69, 0, 0x1c000
	v_add_u32_e32 v142, s68, v199
	v_add_u32_e32 v162, s69, v199
	ds_read_b128 v[130:133], v142
	ds_read_b128 v[134:137], v142 offset:1024
	ds_read_b128 v[138:141], v142 offset:2048
	ds_read_b128 v[142:145], v142 offset:3072
	ds_read_b128 v[146:149], v162
	ds_read_b128 v[150:153], v162 offset:1024
	ds_read_b128 v[154:157], v162 offset:2048
	ds_read_b128 v[162:165], v162 offset:3072
	s_add_u32 s36, s36, 0x200000
	s_addc_u32 s37, s37, 0
	s_mov_b32 m0, s51
	s_nop 0
	global_load_lds_dwordx4 v[220:221], off
	s_mov_b32 m0, s52
	s_nop 0
	global_load_lds_dwordx4 v[222:223], off
	s_mov_b32 m0, s53
	v_lshl_add_u64 v[224:225], s[36:37], 0, v[170:171]
	ds_read_b128 v[176:179], v201 offset:32768
	ds_read_b128 v[180:183], v201 offset:33792
	ds_read_b128 v[184:187], v201 offset:34816
	ds_read_b128 v[188:191], v201 offset:35840
	ds_read_b128 v[202:205], v201 offset:36864
	ds_read_b128 v[206:209], v201 offset:37888
	ds_read_b128 v[210:213], v201 offset:38912
	ds_read_b128 v[214:217], v201 offset:39936
	global_load_lds_dwordx4 v[224:225], off
	v_lshl_add_u64 v[224:225], s[36:37], 0, v[168:169]
	s_mov_b32 m0, s54
	s_nop 0
	global_load_lds_dwordx4 v[224:225], off
	s_waitcnt vmcnt(8)
	s_waitcnt lgkmcnt(0)
	s_barrier
; #define PG8_STAGE(bufoff, gbase, voff) do { _Pragma("unroll") for (int _i = 0; _i < 2; ++_i) \
;         __builtin_amdgcn_global_load_lds((const unsigned*)((const char*)(gbase) + (voff)[_i]), (PG8_LAS unsigned*)(lds + (bufoff) + ldsw + _i * 8192), 16, 0, 0); } while (0)
; #define PG8_LDA(dst, b, h) do { _Pragma("unroll") for (int m = 0; m < 4; ++m) _Pragma("unroll") for (int k = 0; k < 2; ++k) dst[m][k] = *(const PG8_LAS bf16x8*)(lds + PG8_SA(b, h) + aoff + m * 2048 + k * 1024); } while (0)
; #define PG8_MMA(ai, bj, At, Bt) do { __builtin_amdgcn_s_setprio(1); _Pragma("unroll") for (int m = 0; m < 4; ++m) _Pragma("unroll") for (int n = 0; n < 2; ++n) _Pragma("unroll") for (int k = 0; k < 2; ++k) \
;         acc[ai][bj][m][n] = __builtin_amdgcn_mfma_f32_16x16x32_bf16(Bt[n][k], At[m][k], acc[ai][bj][m][n], 0, 0, 0); __builtin_amdgcn_s_setprio(0); } while (0)
; #define PG8_WAIT_V(n) asm volatile("s_waitcnt vmcnt(" #n ")" ::: "memory")
; #define PG8_WAIT_L(n) asm volatile("s_waitcnt lgkmcnt(" #n ")" ::: "memory")
; #define PG8_BAR __builtin_amdgcn_s_barrier()
; #define PG8_SCHED __builtin_amdgcn_sched_barrier(0)
; template <class Epi, class Sched, bool ALIGN_EPI = false, bool SP2 = false>
; __device__ __forceinline__ void gemm_phase(PG8_LAS unsigned char* lds, const Gemm g, const Sched& S, const Epi& E) {
;     ...
;             PG8_WAIT_V(8); PG8_WAIT_L(0); PG8_BAR; PG8_MMA(0, 0, At, B0); PG8_MMA(0, 1, At, B1); PG8_BAR; PG8_SCHED;
;             PG8_LDA(At, 1, 1); PG8_STAGE(PG8_SB(1, 0), b3, voffB); PG8_STAGE(PG8_SB(1, 1), b3 + hstep, voffB); PG8_STAGE(PG8_SA(1, 0), a3, voffA);
;             PG8_WAIT_V(8); PG8_WAIT_L(0); PG8_BAR; PG8_MMA(1, 0, At, B0); PG8_MMA(1, 1, At, B1); PG8_BAR; PG8_SCHED;
	s_setprio 1
	s_waitcnt lgkmcnt(0)
	v_mfma_f32_16x16x32_bf16 v[126:129], v[130:133], v[176:179], v[126:129]
	v_mfma_f32_16x16x32_bf16 v[122:125], v[138:141], v[176:179], v[122:125]
	v_mfma_f32_16x16x32_bf16 v[110:113], v[130:133], v[184:187], v[110:113]
	v_mfma_f32_16x16x32_bf16 v[106:109], v[138:141], v[184:187], v[106:109]
	v_mfma_f32_16x16x32_bf16 v[94:97], v[130:133], v[202:205], v[94:97]
	v_mfma_f32_16x16x32_bf16 v[90:93], v[138:141], v[202:205], v[90:93]
	v_mfma_f32_16x16x32_bf16 v[78:81], v[130:133], v[210:213], v[78:81]
	v_mfma_f32_16x16x32_bf16 v[74:77], v[138:141], v[210:213], v[74:77]
	v_mfma_f32_16x16x32_bf16 v[126:129], v[134:137], v[180:183], v[126:129]
	v_mfma_f32_16x16x32_bf16 v[122:125], v[142:145], v[180:183], v[122:125]
	v_mfma_f32_16x16x32_bf16 v[110:113], v[134:137], v[188:191], v[110:113]
	v_mfma_f32_16x16x32_bf16 v[106:109], v[142:145], v[188:191], v[106:109]
	v_mfma_f32_16x16x32_bf16 v[94:97], v[134:137], v[206:209], v[94:97]
	v_mfma_f32_16x16x32_bf16 v[90:93], v[142:145], v[206:209], v[90:93]
	v_mfma_f32_16x16x32_bf16 v[78:81], v[134:137], v[214:217], v[78:81]
	v_mfma_f32_16x16x32_bf16 v[74:77], v[142:145], v[214:217], v[74:77]
	s_setprio 0
	s_setprio 1
	v_mfma_f32_16x16x32_bf16 v[118:121], v[146:149], v[176:179], v[118:121]
	v_mfma_f32_16x16x32_bf16 v[114:117], v[154:157], v[176:179], v[114:117]
	v_mfma_f32_16x16x32_bf16 v[102:105], v[146:149], v[184:187], v[102:105]
	v_mfma_f32_16x16x32_bf16 v[98:101], v[154:157], v[184:187], v[98:101]
	v_mfma_f32_16x16x32_bf16 v[86:89], v[146:149], v[202:205], v[86:89]
	v_mfma_f32_16x16x32_bf16 v[82:85], v[154:157], v[202:205], v[82:85]
	v_mfma_f32_16x16x32_bf16 v[70:73], v[146:149], v[210:213], v[70:73]
	v_mfma_f32_16x16x32_bf16 v[66:69], v[154:157], v[210:213], v[66:69]
	v_mfma_f32_16x16x32_bf16 v[118:121], v[150:153], v[180:183], v[118:121]
	v_mfma_f32_16x16x32_bf16 v[114:117], v[162:165], v[180:183], v[114:117]
	v_mfma_f32_16x16x32_bf16 v[102:105], v[150:153], v[188:191], v[102:105]
	v_mfma_f32_16x16x32_bf16 v[98:101], v[162:165], v[188:191], v[98:101]
	v_mfma_f32_16x16x32_bf16 v[86:89], v[150:153], v[206:209], v[86:89]
	v_mfma_f32_16x16x32_bf16 v[82:85], v[162:165], v[206:209], v[82:85]
	v_mfma_f32_16x16x32_bf16 v[70:73], v[150:153], v[214:217], v[70:73]
	v_mfma_f32_16x16x32_bf16 v[66:69], v[162:165], v[214:217], v[66:69]
	s_setprio 0
	s_barrier
	s_add_i32 s36, s68, s50
	v_lshl_add_u64 v[192:193], v[192:193], 0, s[10:11]
	s_mov_b32 m0, s36
	ds_read_b128 v[176:179], v201 offset:49152
	ds_read_b128 v[180:183], v201 offset:50176
	ds_read_b128 v[184:187], v201 offset:51200
	ds_read_b128 v[188:191], v201 offset:52224
	ds_read_b128 v[202:205], v201 offset:53248
	ds_read_b128 v[206:209], v201 offset:54272
	ds_read_b128 v[210:213], v201 offset:55296
	ds_read_b128 v[214:217], v201 offset:56320
	global_load_lds_dwordx4 v[192:193], off
	s_add_i32 m0, s36, 0x2000
	s_add_u32 s30, s30, 0x200080
	v_lshl_add_u64 v[192:193], v[218:219], 0, s[10:11]
	s_addc_u32 s31, s31, 0
	s_add_i32 s36, s69, s50
	global_load_lds_dwordx4 v[192:193], off
	v_lshl_add_u64 v[192:193], s[30:31], 0, v[158:159]
	s_mov_b32 m0, s36
	s_nop 0
	global_load_lds_dwordx4 v[192:193], off
	v_lshl_add_u64 v[192:193], s[30:31], 0, v[166:167]
	s_add_i32 m0, s36, 0x2000
	s_nop 0
	global_load_lds_dwordx4 v[192:193], off
	s_waitcnt vmcnt(6)
	s_waitcnt lgkmcnt(0)
	s_barrier
	s_setprio 1
	s_waitcnt lgkmcnt(0)
	v_mfma_f32_16x16x32_bf16 v[62:65], v[130:133], v[176:179], v[62:65]
	v_mfma_f32_16x16x32_bf16 v[58:61], v[138:141], v[176:179], v[58:61]
	v_mfma_f32_16x16x32_bf16 v[46:49], v[130:133], v[184:187], v[46:49]
	v_mfma_f32_16x16x32_bf16 v[42:45], v[138:141], v[184:187], v[42:45]
	v_mfma_f32_16x16x32_bf16 v[30:33], v[130:133], v[202:205], v[30:33]
	v_mfma_f32_16x16x32_bf16 v[26:29], v[138:141], v[202:205], v[26:29]
	v_mfma_f32_16x16x32_bf16 v[14:17], v[130:133], v[210:213], v[14:17]
	v_mfma_f32_16x16x32_bf16 v[10:13], v[138:141], v[210:213], v[10:13]
	v_mfma_f32_16x16x32_bf16 v[62:65], v[134:137], v[180:183], v[62:65]
	v_mfma_f32_16x16x32_bf16 v[58:61], v[142:145], v[180:183], v[58:61]
	v_mfma_f32_16x16x32_bf16 v[46:49], v[134:137], v[188:191], v[46:49]
	v_mfma_f32_16x16x32_bf16 v[42:45], v[142:145], v[188:191], v[42:45]
	v_mfma_f32_16x16x32_bf16 v[30:33], v[134:137], v[206:209], v[30:33]
	v_mfma_f32_16x16x32_bf16 v[26:29], v[142:145], v[206:209], v[26:29]
	v_mfma_f32_16x16x32_bf16 v[14:17], v[134:137], v[214:217], v[14:17]
	v_mfma_f32_16x16x32_bf16 v[10:13], v[142:145], v[214:217], v[10:13]
	s_setprio 0
	s_setprio 1
	v_mfma_f32_16x16x32_bf16 v[54:57], v[146:149], v[176:179], v[54:57]
	v_mfma_f32_16x16x32_bf16 v[50:53], v[154:157], v[176:179], v[50:53]
	v_mfma_f32_16x16x32_bf16 v[38:41], v[146:149], v[184:187], v[38:41]
	v_mfma_f32_16x16x32_bf16 v[34:37], v[154:157], v[184:187], v[34:37]
	v_mfma_f32_16x16x32_bf16 v[22:25], v[146:149], v[202:205], v[22:25]
	v_mfma_f32_16x16x32_bf16 v[18:21], v[154:157], v[202:205], v[18:21]
	v_mfma_f32_16x16x32_bf16 v[6:9], v[146:149], v[210:213], v[6:9]
	v_mfma_f32_16x16x32_bf16 v[2:5], v[154:157], v[210:213], v[2:5]
	v_mfma_f32_16x16x32_bf16 v[54:57], v[150:153], v[180:183], v[54:57]
	v_mfma_f32_16x16x32_bf16 v[50:53], v[162:165], v[180:183], v[50:53]
	v_mfma_f32_16x16x32_bf16 v[38:41], v[150:153], v[188:191], v[38:41]
	v_mfma_f32_16x16x32_bf16 v[34:37], v[162:165], v[188:191], v[34:37]
	v_mfma_f32_16x16x32_bf16 v[22:25], v[150:153], v[206:209], v[22:25]
	v_mfma_f32_16x16x32_bf16 v[18:21], v[162:165], v[206:209], v[18:21]
	v_mfma_f32_16x16x32_bf16 v[6:9], v[150:153], v[214:217], v[6:9]
	v_mfma_f32_16x16x32_bf16 v[2:5], v[162:165], v[214:217], v[2:5]
	s_setprio 0
	s_barrier
	s_add_i32 s67, s67, 2
	s_add_u32 s0, s0, 0x100
	s_addc_u32 s1, s1, 0
	s_add_u32 s63, s63, 0x100
	s_addc_u32 s66, s66, 0
	s_cmpk_gt_u32 s67, 0x7d
	s_cbranch_scc0 .LBB0_842
	s_and_b64 vcc, exec, s[16:17]
	s_cbranch_vccz .LBB0_845
	s_barrier

; #define PG8_STAGE(bufoff, gbase, voff) do { _Pragma("unroll") for (int _i = 0; _i < 2; ++_i) \
;         __builtin_amdgcn_global_load_lds((const unsigned*)((const char*)(gbase) + (voff)[_i]), (PG8_LAS unsigned*)(lds + (bufoff) + ldsw + _i * 8192), 16, 0, 0); } while (0)
; #define PG8_LDA(dst, b, h) do { _Pragma("unroll") for (int m = 0; m < 4; ++m) _Pragma("unroll") for (int k = 0; k < 2; ++k) dst[m][k] = *(const PG8_LAS bf16x8*)(lds + PG8_SA(b, h) + aoff + m * 2048 + k * 1024); } while (0)
; #define PG8_LDB(dst, b, h) do { _Pragma("unroll") for (int n = 0; n < 2; ++n) _Pragma("unroll") for (int k = 0; k < 2; ++k) dst[n][k] = *(const PG8_LAS bf16x8*)(lds + PG8_SB(b, h) + boff + n * 2048 + k * 1024); } while (0)
; #define PG8_MMA(ai, bj, At, Bt) do { __builtin_amdgcn_s_setprio(1); _Pragma("unroll") for (int m = 0; m < 4; ++m) _Pragma("unroll") for (int n = 0; n < 2; ++n) _Pragma("unroll") for (int k = 0; k < 2; ++k) \
;         acc[ai][bj][m][n] = __builtin_amdgcn_mfma_f32_16x16x32_bf16(Bt[n][k], At[m][k], acc[ai][bj][m][n], 0, 0, 0); __builtin_amdgcn_s_setprio(0); } while (0)
; #define PG8_WAIT_V(n) asm volatile("s_waitcnt vmcnt(" #n ")" ::: "memory")
; #define PG8_WAIT_L(n) asm volatile("s_waitcnt lgkmcnt(" #n ")" ::: "memory")
; #define PG8_BAR __builtin_amdgcn_s_barrier()
; #define PG8_SCHED __builtin_amdgcn_sched_barrier(0)
; template <class Epi, class Sched, bool ALIGN_EPI = false, bool SP2 = false>
; __device__ __forceinline__ void gemm_phase(PG8_LAS unsigned char* lds, const Gemm g, const Sched& S, const Epi& E) {
;     ...
;             PG8_LDB(B0, 0, 0); PG8_LDB(B1, 0, 1); PG8_SCHED; PG8_LDA(At, 0, 0); PG8_STAGE(PG8_SA(1, 1), a1 + hstep, voffA);
;             PG8_WAIT_V(8); PG8_WAIT_L(0); PG8_BAR; PG8_MMA(0, 0, At, B0); PG8_MMA(0, 1, At, B1); PG8_BAR; PG8_SCHED;
;             PG8_LDA(At, 0, 1); PG8_STAGE(PG8_SB(0, 0), b2, voffB); PG8_STAGE(PG8_SB(0, 1), b2 + hstep, voffB); PG8_STAGE(PG8_SA(0, 0), a2, voffA);
;             PG8_WAIT_V(8); PG8_WAIT_L(0); PG8_BAR; PG8_MMA(1, 0, At, B0); PG8_MMA(1, 1, At, B1); PG8_BAR; PG8_SCHED;
.LBB0_880:
	s_add_u32 s28, s0, 0xffe00080
	s_addc_u32 s29, s1, -1
	s_add_i32 s59, 0, 0x10000
	s_cmpk_eq_i32 s58, 0x7c
	s_cselect_b32 s31, s19, s29
	s_cselect_b32 s30, s54, s28
	s_cselect_b32 s29, s17, s57
	s_cselect_b32 s28, s55, s56
	s_add_i32 s62, 0, 0x14000
	v_add_u32_e32 v142, s59, v178
	v_add_u32_e32 v172, s62, v178
	ds_read_b128 v[130:133], v142
	ds_read_b128 v[134:137], v142 offset:1024
	ds_read_b128 v[138:141], v142 offset:2048
	ds_read_b128 v[142:145], v142 offset:3072
	ds_read_b128 v[146:149], v172
	ds_read_b128 v[162:165], v172 offset:1024
	ds_read_b128 v[168:171], v172 offset:2048
	ds_read_b128 v[172:175], v172 offset:3072
	s_add_u32 s98, s0, 0xffe00000
	s_addc_u32 s99, s1, -1
	v_lshl_add_u64 v[176:177], s[98:99], 0, v[156:157]
	s_mov_b32 m0, s44
	s_nop 0
	global_load_lds_dwordx4 v[176:177], off
	v_lshl_add_u64 v[176:177], s[98:99], 0, v[166:167]
	s_mov_b32 m0, s45
	s_nop 0
	global_load_lds_dwordx4 v[176:177], off
	v_lshl_add_u64 v[176:177], s[0:1], 0, v[156:157]
	s_add_i32 m0, s36, 0xc000
	ds_read_b128 v[182:185], v180
	ds_read_b128 v[186:189], v180 offset:1024
	ds_read_b128 v[190:193], v180 offset:2048
	ds_read_b128 v[200:203], v180 offset:3072
	ds_read_b128 v[204:207], v180 offset:4096
	ds_read_b128 v[208:211], v180 offset:5120
	ds_read_b128 v[212:215], v180 offset:6144
	ds_read_b128 v[216:219], v180 offset:7168
	global_load_lds_dwordx4 v[176:177], off
	v_lshl_add_u64 v[176:177], s[0:1], 0, v[166:167]
	s_add_i32 m0, s36, 0xe000
	s_nop 0
	global_load_lds_dwordx4 v[176:177], off
	s_waitcnt vmcnt(8)
	s_waitcnt lgkmcnt(0)
	s_barrier
	s_setprio 1
	s_waitcnt lgkmcnt(0)
	v_mfma_f32_16x16x32_bf16 v[126:129], v[130:133], v[182:185], v[126:129]
	v_mfma_f32_16x16x32_bf16 v[122:125], v[138:141], v[182:185], v[122:125]
	v_mfma_f32_16x16x32_bf16 v[118:121], v[130:133], v[190:193], v[118:121]
	v_mfma_f32_16x16x32_bf16 v[114:117], v[138:141], v[190:193], v[114:117]
	v_mfma_f32_16x16x32_bf16 v[94:97], v[130:133], v[204:207], v[94:97]
	v_mfma_f32_16x16x32_bf16 v[90:93], v[138:141], v[204:207], v[90:93]
	v_mfma_f32_16x16x32_bf16 v[82:85], v[130:133], v[212:215], v[82:85]
	v_mfma_f32_16x16x32_bf16 v[74:77], v[138:141], v[212:215], v[74:77]
	v_mfma_f32_16x16x32_bf16 v[126:129], v[134:137], v[186:189], v[126:129]
	v_mfma_f32_16x16x32_bf16 v[122:125], v[142:145], v[186:189], v[122:125]
	v_mfma_f32_16x16x32_bf16 v[118:121], v[134:137], v[200:203], v[118:121]
	v_mfma_f32_16x16x32_bf16 v[114:117], v[142:145], v[200:203], v[114:117]
	v_mfma_f32_16x16x32_bf16 v[94:97], v[134:137], v[208:211], v[94:97]
	v_mfma_f32_16x16x32_bf16 v[90:93], v[142:145], v[208:211], v[90:93]
	v_mfma_f32_16x16x32_bf16 v[82:85], v[134:137], v[216:219], v[82:85]
	v_mfma_f32_16x16x32_bf16 v[74:77], v[142:145], v[216:219], v[74:77]
	s_setprio 0
	s_setprio 1
	v_mfma_f32_16x16x32_bf16 v[110:113], v[146:149], v[182:185], v[110:113]
	v_mfma_f32_16x16x32_bf16 v[106:109], v[168:171], v[182:185], v[106:109]
	v_mfma_f32_16x16x32_bf16 v[102:105], v[146:149], v[190:193], v[102:105]
	v_mfma_f32_16x16x32_bf16 v[98:101], v[168:171], v[190:193], v[98:101]
	v_mfma_f32_16x16x32_bf16 v[86:89], v[146:149], v[204:207], v[86:89]
	v_mfma_f32_16x16x32_bf16 v[78:81], v[168:171], v[204:207], v[78:81]
	v_mfma_f32_16x16x32_bf16 v[70:73], v[146:149], v[212:215], v[70:73]
	v_mfma_f32_16x16x32_bf16 v[66:69], v[168:171], v[212:215], v[66:69]
	v_mfma_f32_16x16x32_bf16 v[110:113], v[162:165], v[186:189], v[110:113]
	v_mfma_f32_16x16x32_bf16 v[106:109], v[172:175], v[186:189], v[106:109]
	v_mfma_f32_16x16x32_bf16 v[102:105], v[162:165], v[200:203], v[102:105]
	v_mfma_f32_16x16x32_bf16 v[98:101], v[172:175], v[200:203], v[98:101]
	v_mfma_f32_16x16x32_bf16 v[86:89], v[162:165], v[208:211], v[86:89]
	v_mfma_f32_16x16x32_bf16 v[78:81], v[172:175], v[208:211], v[78:81]
	v_mfma_f32_16x16x32_bf16 v[70:73], v[162:165], v[216:219], v[70:73]
	v_mfma_f32_16x16x32_bf16 v[66:69], v[172:175], v[216:219], v[66:69]
	s_setprio 0
	s_barrier
	s_add_i32 s59, s59, s34
	v_lshl_add_u64 v[176:177], s[28:29], 0, v[158:159]
	s_mov_b32 m0, s59
	ds_read_b128 v[182:185], v180 offset:16384
	ds_read_b128 v[186:189], v180 offset:17408
	ds_read_b128 v[190:193], v180 offset:18432
	ds_read_b128 v[200:203], v180 offset:19456
	ds_read_b128 v[204:207], v180 offset:20480
	ds_read_b128 v[208:211], v180 offset:21504
	ds_read_b128 v[212:215], v180 offset:22528
	ds_read_b128 v[216:219], v180 offset:23552
	global_load_lds_dwordx4 v[176:177], off
	s_add_i32 m0, s59, 0x2000
	s_add_u32 s60, s28, 0x200000
	v_lshl_add_u64 v[220:221], s[28:29], 0, v[150:151]
	s_addc_u32 s61, s29, 0
	s_add_i32 s59, s62, s34
	global_load_lds_dwordx4 v[220:221], off
	v_lshl_add_u64 v[222:223], s[60:61], 0, v[158:159]
	s_mov_b32 m0, s59
	v_lshl_add_u64 v[224:225], s[30:31], 0, v[152:153]
	global_load_lds_dwordx4 v[222:223], off
	v_lshl_add_u64 v[222:223], s[60:61], 0, v[150:151]
	s_add_i32 m0, s59, 0x2000
	s_nop 0
	global_load_lds_dwordx4 v[222:223], off
	v_lshl_add_u64 v[222:223], s[30:31], 0, v[154:155]
	s_waitcnt vmcnt(6)
	s_waitcnt lgkmcnt(0)
	s_barrier
; #define PG8_STAGE(bufoff, gbase, voff) do { _Pragma("unroll") for (int _i = 0; _i < 2; ++_i) \
;         __builtin_amdgcn_global_load_lds((const unsigned*)((const char*)(gbase) + (voff)[_i]), (PG8_LAS unsigned*)(lds + (bufoff) + ldsw + _i * 8192), 16, 0, 0); } while (0)
; #define PG8_LDA(dst, b, h) do { _Pragma("unroll") for (int m = 0; m < 4; ++m) _Pragma("unroll") for (int k = 0; k < 2; ++k) dst[m][k] = *(const PG8_LAS bf16x8*)(lds + PG8_SA(b, h) + aoff + m * 2048 + k * 1024); } while (0)
; #define PG8_LDB(dst, b, h) do { _Pragma("unroll") for (int n = 0; n < 2; ++n) _Pragma("unroll") for (int k = 0; k < 2; ++k) dst[n][k] = *(const PG8_LAS bf16x8*)(lds + PG8_SB(b, h) + boff + n * 2048 + k * 1024); } while (0)
; #define PG8_MMA(ai, bj, At, Bt) do { __builtin_amdgcn_s_setprio(1); _Pragma("unroll") for (int m = 0; m < 4; ++m) _Pragma("unroll") for (int n = 0; n < 2; ++n) _Pragma("unroll") for (int k = 0; k < 2; ++k) \
;         acc[ai][bj][m][n] = __builtin_amdgcn_mfma_f32_16x16x32_bf16(Bt[n][k], At[m][k], acc[ai][bj][m][n], 0, 0, 0); __builtin_amdgcn_s_setprio(0); } while (0)
; #define PG8_WAIT_V(n) asm volatile("s_waitcnt vmcnt(" #n ")" ::: "memory")
; #define PG8_WAIT_L(n) asm volatile("s_waitcnt lgkmcnt(" #n ")" ::: "memory")
; #define PG8_BAR __builtin_amdgcn_s_barrier()
; #define PG8_SCHED __builtin_amdgcn_sched_barrier(0)
; template <class Epi, class Sched, bool ALIGN_EPI = false, bool SP2 = false>
; __device__ __forceinline__ void gemm_phase(PG8_LAS unsigned char* lds, const Gemm g, const Sched& S, const Epi& E) {
;     ...
;             PG8_WAIT_V(8); PG8_WAIT_L(0); PG8_BAR; PG8_MMA(1, 0, At, B0); PG8_MMA(1, 1, At, B1); PG8_BAR; PG8_SCHED;
;             PG8_LDB(B0, 1, 0); PG8_LDB(B1, 1, 1); PG8_SCHED; PG8_LDA(At, 1, 0); PG8_STAGE(PG8_SA(0, 1), a2 + hstep, voffA);
;             PG8_WAIT_V(8); PG8_WAIT_L(0); PG8_BAR; PG8_MMA(0, 0, At, B0); PG8_MMA(0, 1, At, B1); PG8_BAR; PG8_SCHED;
	s_setprio 1
	s_waitcnt lgkmcnt(0)
	v_mfma_f32_16x16x32_bf16 v[62:65], v[130:133], v[182:185], v[62:65]
	v_mfma_f32_16x16x32_bf16 v[58:61], v[138:141], v[182:185], v[58:61]
	v_mfma_f32_16x16x32_bf16 v[50:53], v[130:133], v[190:193], v[50:53]
	v_mfma_f32_16x16x32_bf16 v[42:45], v[138:141], v[190:193], v[42:45]
	v_mfma_f32_16x16x32_bf16 v[34:37], v[130:133], v[204:207], v[34:37]
	v_mfma_f32_16x16x32_bf16 v[26:29], v[138:141], v[204:207], v[26:29]
	v_mfma_f32_16x16x32_bf16 v[18:21], v[130:133], v[212:215], v[18:21]
	v_mfma_f32_16x16x32_bf16 v[10:13], v[138:141], v[212:215], v[10:13]
	v_mfma_f32_16x16x32_bf16 v[62:65], v[134:137], v[186:189], v[62:65]
	v_mfma_f32_16x16x32_bf16 v[58:61], v[142:145], v[186:189], v[58:61]
	v_mfma_f32_16x16x32_bf16 v[50:53], v[134:137], v[200:203], v[50:53]
	v_mfma_f32_16x16x32_bf16 v[42:45], v[142:145], v[200:203], v[42:45]
	v_mfma_f32_16x16x32_bf16 v[34:37], v[134:137], v[208:211], v[34:37]
	v_mfma_f32_16x16x32_bf16 v[26:29], v[142:145], v[208:211], v[26:29]
	v_mfma_f32_16x16x32_bf16 v[18:21], v[134:137], v[216:219], v[18:21]
	v_mfma_f32_16x16x32_bf16 v[10:13], v[142:145], v[216:219], v[10:13]
	s_setprio 0
	s_setprio 1
	v_mfma_f32_16x16x32_bf16 v[54:57], v[146:149], v[182:185], v[54:57]
	v_mfma_f32_16x16x32_bf16 v[46:49], v[168:171], v[182:185], v[46:49]
	v_mfma_f32_16x16x32_bf16 v[38:41], v[146:149], v[190:193], v[38:41]
	v_mfma_f32_16x16x32_bf16 v[30:33], v[168:171], v[190:193], v[30:33]
	v_mfma_f32_16x16x32_bf16 v[22:25], v[146:149], v[204:207], v[22:25]
	v_mfma_f32_16x16x32_bf16 v[14:17], v[168:171], v[204:207], v[14:17]
	v_mfma_f32_16x16x32_bf16 v[6:9], v[146:149], v[212:215], v[6:9]
	v_mfma_f32_16x16x32_bf16 v[2:5], v[168:171], v[212:215], v[2:5]
	v_mfma_f32_16x16x32_bf16 v[54:57], v[162:165], v[186:189], v[54:57]
	v_mfma_f32_16x16x32_bf16 v[46:49], v[172:175], v[186:189], v[46:49]
	v_mfma_f32_16x16x32_bf16 v[38:41], v[162:165], v[200:203], v[38:41]
	v_mfma_f32_16x16x32_bf16 v[30:33], v[172:175], v[200:203], v[30:33]
	v_mfma_f32_16x16x32_bf16 v[22:25], v[162:165], v[208:211], v[22:25]
	v_mfma_f32_16x16x32_bf16 v[14:17], v[172:175], v[208:211], v[14:17]
	v_mfma_f32_16x16x32_bf16 v[6:9], v[162:165], v[216:219], v[6:9]
	v_mfma_f32_16x16x32_bf16 v[2:5], v[172:175], v[216:219], v[2:5]
	s_setprio 0
	s_barrier
	s_add_i32 s59, 0, 0x18000
	s_add_i32 s60, 0, 0x1c000
	v_add_u32_e32 v142, s59, v178
	v_add_u32_e32 v172, s60, v178
	ds_read_b128 v[130:133], v142
	ds_read_b128 v[134:137], v142 offset:1024
	ds_read_b128 v[138:141], v142 offset:2048
	ds_read_b128 v[142:145], v142 offset:3072
	ds_read_b128 v[146:149], v172
	ds_read_b128 v[162:165], v172 offset:1024
	ds_read_b128 v[168:171], v172 offset:2048
	ds_read_b128 v[172:175], v172 offset:3072
	s_add_u32 s30, s30, 0x200000
	s_addc_u32 s31, s31, 0
	s_mov_b32 m0, s36
	s_nop 0
	global_load_lds_dwordx4 v[222:223], off
	s_mov_b32 m0, s37
	s_nop 0
	global_load_lds_dwordx4 v[224:225], off
	s_mov_b32 m0, s42
	v_lshl_add_u64 v[226:227], s[30:31], 0, v[154:155]
	ds_read_b128 v[182:185], v180 offset:32768
	ds_read_b128 v[186:189], v180 offset:33792
	ds_read_b128 v[190:193], v180 offset:34816
	ds_read_b128 v[200:203], v180 offset:35840
	ds_read_b128 v[204:207], v180 offset:36864
	ds_read_b128 v[208:211], v180 offset:37888
	ds_read_b128 v[212:215], v180 offset:38912
	ds_read_b128 v[216:219], v180 offset:39936
	global_load_lds_dwordx4 v[226:227], off
	v_lshl_add_u64 v[226:227], s[30:31], 0, v[152:153]
	s_mov_b32 m0, s43
	s_nop 0
	global_load_lds_dwordx4 v[226:227], off
	s_waitcnt vmcnt(8)
	s_waitcnt lgkmcnt(0)
	s_barrier
; #define PG8_STAGE(bufoff, gbase, voff) do { _Pragma("unroll") for (int _i = 0; _i < 2; ++_i) \
;         __builtin_amdgcn_global_load_lds((const unsigned*)((const char*)(gbase) + (voff)[_i]), (PG8_LAS unsigned*)(lds + (bufoff) + ldsw + _i * 8192), 16, 0, 0); } while (0)
; #define PG8_LDA(dst, b, h) do { _Pragma("unroll") for (int m = 0; m < 4; ++m) _Pragma("unroll") for (int k = 0; k < 2; ++k) dst[m][k] = *(const PG8_LAS bf16x8*)(lds + PG8_SA(b, h) + aoff + m * 2048 + k * 1024); } while (0)
; #define PG8_MMA(ai, bj, At, Bt) do { __builtin_amdgcn_s_setprio(1); _Pragma("unroll") for (int m = 0; m < 4; ++m) _Pragma("unroll") for (int n = 0; n < 2; ++n) _Pragma("unroll") for (int k = 0; k < 2; ++k) \
;         acc[ai][bj][m][n] = __builtin_amdgcn_mfma_f32_16x16x32_bf16(Bt[n][k], At[m][k], acc[ai][bj][m][n], 0, 0, 0); __builtin_amdgcn_s_setprio(0); } while (0)
; #define PG8_WAIT_V(n) asm volatile("s_waitcnt vmcnt(" #n ")" ::: "memory")
; #define PG8_WAIT_L(n) asm volatile("s_waitcnt lgkmcnt(" #n ")" ::: "memory")
; #define PG8_BAR __builtin_amdgcn_s_barrier()
; #define PG8_SCHED __builtin_amdgcn_sched_barrier(0)
; template <class Epi, class Sched, bool ALIGN_EPI = false, bool SP2 = false>
; __device__ __forceinline__ void gemm_phase(PG8_LAS unsigned char* lds, const Gemm g, const Sched& S, const Epi& E) {
;     ...
;             PG8_WAIT_V(8); PG8_WAIT_L(0); PG8_BAR; PG8_MMA(0, 0, At, B0); PG8_MMA(0, 1, At, B1); PG8_BAR; PG8_SCHED;
;             PG8_LDA(At, 1, 1); PG8_STAGE(PG8_SB(1, 0), b3, voffB); PG8_STAGE(PG8_SB(1, 1), b3 + hstep, voffB); PG8_STAGE(PG8_SA(1, 0), a3, voffA);
;             PG8_WAIT_V(8); PG8_WAIT_L(0); PG8_BAR; PG8_MMA(1, 0, At, B0); PG8_MMA(1, 1, At, B1); PG8_BAR; PG8_SCHED;
	s_setprio 1
	s_waitcnt lgkmcnt(0)
	v_mfma_f32_16x16x32_bf16 v[126:129], v[130:133], v[182:185], v[126:129]
	v_mfma_f32_16x16x32_bf16 v[122:125], v[138:141], v[182:185], v[122:125]
	v_mfma_f32_16x16x32_bf16 v[118:121], v[130:133], v[190:193], v[118:121]
	v_mfma_f32_16x16x32_bf16 v[114:117], v[138:141], v[190:193], v[114:117]
	v_mfma_f32_16x16x32_bf16 v[94:97], v[130:133], v[204:207], v[94:97]
	v_mfma_f32_16x16x32_bf16 v[90:93], v[138:141], v[204:207], v[90:93]
	v_mfma_f32_16x16x32_bf16 v[82:85], v[130:133], v[212:215], v[82:85]
	v_mfma_f32_16x16x32_bf16 v[74:77], v[138:141], v[212:215], v[74:77]
	v_mfma_f32_16x16x32_bf16 v[126:129], v[134:137], v[186:189], v[126:129]
	v_mfma_f32_16x16x32_bf16 v[122:125], v[142:145], v[186:189], v[122:125]
	v_mfma_f32_16x16x32_bf16 v[118:121], v[134:137], v[200:203], v[118:121]
	v_mfma_f32_16x16x32_bf16 v[114:117], v[142:145], v[200:203], v[114:117]
	v_mfma_f32_16x16x32_bf16 v[94:97], v[134:137], v[208:211], v[94:97]
	v_mfma_f32_16x16x32_bf16 v[90:93], v[142:145], v[208:211], v[90:93]
	v_mfma_f32_16x16x32_bf16 v[82:85], v[134:137], v[216:219], v[82:85]
	v_mfma_f32_16x16x32_bf16 v[74:77], v[142:145], v[216:219], v[74:77]
	s_setprio 0
	s_setprio 1
	v_mfma_f32_16x16x32_bf16 v[110:113], v[146:149], v[182:185], v[110:113]
	v_mfma_f32_16x16x32_bf16 v[106:109], v[168:171], v[182:185], v[106:109]
	v_mfma_f32_16x16x32_bf16 v[102:105], v[146:149], v[190:193], v[102:105]
	v_mfma_f32_16x16x32_bf16 v[98:101], v[168:171], v[190:193], v[98:101]
	v_mfma_f32_16x16x32_bf16 v[86:89], v[146:149], v[204:207], v[86:89]
	v_mfma_f32_16x16x32_bf16 v[78:81], v[168:171], v[204:207], v[78:81]
	v_mfma_f32_16x16x32_bf16 v[70:73], v[146:149], v[212:215], v[70:73]
	v_mfma_f32_16x16x32_bf16 v[66:69], v[168:171], v[212:215], v[66:69]
	v_mfma_f32_16x16x32_bf16 v[110:113], v[162:165], v[186:189], v[110:113]
	v_mfma_f32_16x16x32_bf16 v[106:109], v[172:175], v[186:189], v[106:109]
	v_mfma_f32_16x16x32_bf16 v[102:105], v[162:165], v[200:203], v[102:105]
	v_mfma_f32_16x16x32_bf16 v[98:101], v[172:175], v[200:203], v[98:101]
	v_mfma_f32_16x16x32_bf16 v[86:89], v[162:165], v[208:211], v[86:89]
	v_mfma_f32_16x16x32_bf16 v[78:81], v[172:175], v[208:211], v[78:81]
	v_mfma_f32_16x16x32_bf16 v[70:73], v[162:165], v[216:219], v[70:73]
	v_mfma_f32_16x16x32_bf16 v[66:69], v[172:175], v[216:219], v[66:69]
	s_setprio 0
	s_barrier
	s_add_i32 s30, s59, s34
	v_lshl_add_u64 v[176:177], v[176:177], 0, s[10:11]
	s_mov_b32 m0, s30
	ds_read_b128 v[182:185], v180 offset:49152
	ds_read_b128 v[186:189], v180 offset:50176
	ds_read_b128 v[190:193], v180 offset:51200
	ds_read_b128 v[200:203], v180 offset:52224
	ds_read_b128 v[204:207], v180 offset:53248
	ds_read_b128 v[208:211], v180 offset:54272
	ds_read_b128 v[212:215], v180 offset:55296
	ds_read_b128 v[216:219], v180 offset:56320
	global_load_lds_dwordx4 v[176:177], off
	s_add_i32 m0, s30, 0x2000
	s_add_u32 s28, s28, 0x200080
	v_lshl_add_u64 v[176:177], v[220:221], 0, s[10:11]
	s_addc_u32 s29, s29, 0
	s_add_i32 s30, s60, s34
	global_load_lds_dwordx4 v[176:177], off
	v_lshl_add_u64 v[176:177], s[28:29], 0, v[158:159]
	s_mov_b32 m0, s30
	s_nop 0
	global_load_lds_dwordx4 v[176:177], off
	v_lshl_add_u64 v[176:177], s[28:29], 0, v[150:151]
	s_add_i32 m0, s30, 0x2000
	s_nop 0
	global_load_lds_dwordx4 v[176:177], off
	s_waitcnt vmcnt(6)
	s_waitcnt lgkmcnt(0)
	s_barrier
	s_setprio 1
	s_waitcnt lgkmcnt(0)
	v_mfma_f32_16x16x32_bf16 v[62:65], v[130:133], v[182:185], v[62:65]
	v_mfma_f32_16x16x32_bf16 v[58:61], v[138:141], v[182:185], v[58:61]
	v_mfma_f32_16x16x32_bf16 v[50:53], v[130:133], v[190:193], v[50:53]
	v_mfma_f32_16x16x32_bf16 v[42:45], v[138:141], v[190:193], v[42:45]
	v_mfma_f32_16x16x32_bf16 v[34:37], v[130:133], v[204:207], v[34:37]
	v_mfma_f32_16x16x32_bf16 v[26:29], v[138:141], v[204:207], v[26:29]
	v_mfma_f32_16x16x32_bf16 v[18:21], v[130:133], v[212:215], v[18:21]
	v_mfma_f32_16x16x32_bf16 v[10:13], v[138:141], v[212:215], v[10:13]
	v_mfma_f32_16x16x32_bf16 v[62:65], v[134:137], v[186:189], v[62:65]
	v_mfma_f32_16x16x32_bf16 v[58:61], v[142:145], v[186:189], v[58:61]
	v_mfma_f32_16x16x32_bf16 v[50:53], v[134:137], v[200:203], v[50:53]
	v_mfma_f32_16x16x32_bf16 v[42:45], v[142:145], v[200:203], v[42:45]
	v_mfma_f32_16x16x32_bf16 v[34:37], v[134:137], v[208:211], v[34:37]
	v_mfma_f32_16x16x32_bf16 v[26:29], v[142:145], v[208:211], v[26:29]
	v_mfma_f32_16x16x32_bf16 v[18:21], v[134:137], v[216:219], v[18:21]
	v_mfma_f32_16x16x32_bf16 v[10:13], v[142:145], v[216:219], v[10:13]
	s_setprio 0
	s_setprio 1
	v_mfma_f32_16x16x32_bf16 v[54:57], v[146:149], v[182:185], v[54:57]
	v_mfma_f32_16x16x32_bf16 v[46:49], v[168:171], v[182:185], v[46:49]
	v_mfma_f32_16x16x32_bf16 v[38:41], v[146:149], v[190:193], v[38:41]
	v_mfma_f32_16x16x32_bf16 v[30:33], v[168:171], v[190:193], v[30:33]
	v_mfma_f32_16x16x32_bf16 v[22:25], v[146:149], v[204:207], v[22:25]
	v_mfma_f32_16x16x32_bf16 v[14:17], v[168:171], v[204:207], v[14:17]
	v_mfma_f32_16x16x32_bf16 v[6:9], v[146:149], v[212:215], v[6:9]
	v_mfma_f32_16x16x32_bf16 v[2:5], v[168:171], v[212:215], v[2:5]
	v_mfma_f32_16x16x32_bf16 v[54:57], v[162:165], v[186:189], v[54:57]
	v_mfma_f32_16x16x32_bf16 v[46:49], v[172:175], v[186:189], v[46:49]
	v_mfma_f32_16x16x32_bf16 v[38:41], v[162:165], v[200:203], v[38:41]
	v_mfma_f32_16x16x32_bf16 v[30:33], v[172:175], v[200:203], v[30:33]
	v_mfma_f32_16x16x32_bf16 v[22:25], v[162:165], v[208:211], v[22:25]
	v_mfma_f32_16x16x32_bf16 v[14:17], v[172:175], v[208:211], v[14:17]
	v_mfma_f32_16x16x32_bf16 v[6:9], v[162:165], v[216:219], v[6:9]
	v_mfma_f32_16x16x32_bf16 v[2:5], v[172:175], v[216:219], v[2:5]
	s_setprio 0
	s_barrier
	s_add_i32 s58, s58, 2
	s_add_u32 s0, s0, 0x100
	s_addc_u32 s1, s1, 0
	s_add_u32 s56, s56, 0x100
	s_addc_u32 s57, s57, 0
	s_cmpk_gt_u32 s58, 0x7d
	s_cbranch_scc0 .LBB0_880
	s_and_b64 vcc, exec, s[14:15]
	s_cbranch_vccz .LBB0_883
	s_barrier

; __global__ void __launch_bounds__(NTHR, 2) mega_fwd(Args args) {
	.amdhsa_kernel _Z8mega_fwd4Args
		.amdhsa_group_segment_fixed_size 0
		.amdhsa_private_segment_fixed_size 0
		.amdhsa_kernarg_size 392
		.amdhsa_user_sgpr_count 2
		.amdhsa_user_sgpr_dispatch_ptr 0
		.amdhsa_user_sgpr_queue_ptr 0
		.amdhsa_user_sgpr_kernarg_segment_ptr 1
		.amdhsa_user_sgpr_dispatch_id 0
		.amdhsa_user_sgpr_kernarg_preload_length 0
		.amdhsa_user_sgpr_kernarg_preload_offset 0
		.amdhsa_user_sgpr_private_segment_size 0
		.amdhsa_uses_dynamic_stack 0
		.amdhsa_enable_private_segment 0
		.amdhsa_system_sgpr_workgroup_id_x 1
		.amdhsa_system_sgpr_workgroup_id_y 0
		.amdhsa_system_sgpr_workgroup_id_z 0
		.amdhsa_system_sgpr_workgroup_info 0
		.amdhsa_system_vgpr_workitem_id 0
		.amdhsa_next_free_vgpr 255
		.amdhsa_next_free_sgpr 102
		.amdhsa_accum_offset 256
		.amdhsa_reserve_vcc 1
		.amdhsa_float_round_mode_32 0
		.amdhsa_float_round_mode_16_64 0
		.amdhsa_float_denorm_mode_32 3
		.amdhsa_float_denorm_mode_16_64 3
		.amdhsa_dx10_clamp 1
		.amdhsa_ieee_mode 1
		.amdhsa_fp16_overflow 0
		.amdhsa_tg_split 0
		.amdhsa_exception_fp_ieee_invalid_op 0
		.amdhsa_exception_fp_denorm_src 0
		.amdhsa_exception_fp_ieee_div_zero 0
		.amdhsa_exception_fp_ieee_overflow 0
		.amdhsa_exception_fp_ieee_underflow 0
		.amdhsa_exception_fp_ieee_inexact 0
		.amdhsa_exception_int_div_zero 0
	.end_amdhsa_kernel

; __global__ void __launch_bounds__(NTHR, 2) mega_fwd(Args args) {
amdhsa.kernels:
  - .agpr_count:     0
    .args:
      - .offset:         0
        .size:           136
        .value_kind:     by_value
      - .offset:         136
        .size:           4
        .value_kind:     hidden_block_count_x
      - .offset:         140
        .size:           4
        .value_kind:     hidden_block_count_y
      - .offset:         144
        .size:           4
        .value_kind:     hidden_block_count_z
      - .offset:         148
        .size:           2
        .value_kind:     hidden_group_size_x
      - .offset:         150
        .size:           2
        .value_kind:     hidden_group_size_y
      - .offset:         152
        .size:           2
        .value_kind:     hidden_group_size_z
      - .offset:         154
        .size:           2
        .value_kind:     hidden_remainder_x
      - .offset:         156
        .size:           2
        .value_kind:     hidden_remainder_y
      - .offset:         158
        .size:           2
        .value_kind:     hidden_remainder_z
      - .offset:         176
        .size:           8
        .value_kind:     hidden_global_offset_x
      - .offset:         184
        .size:           8
        .value_kind:     hidden_global_offset_y
      - .offset:         192
        .size:           8
        .value_kind:     hidden_global_offset_z
      - .offset:         200
        .size:           2
        .value_kind:     hidden_grid_dims
      - .offset:         256
        .size:           4
        .value_kind:     hidden_dynamic_lds_size
    .group_segment_fixed_size: 0
    .kernarg_segment_align: 8
    .kernarg_segment_size: 392
    .language:       OpenCL C
    .language_version:
      - 2
      - 0
    .max_flat_workgroup_size: 512
    .name:           _Z8mega_fwd4Args
    .private_segment_fixed_size: 0
    .sgpr_count:     108
    .sgpr_spill_count: 159
    .symbol:         _Z8mega_fwd4Args.kd
    .uniform_work_group_size: 1
    .uses_dynamic_stack: false
    .vgpr_count:     255
    .vgpr_spill_count: 0
    .wavefront_size: 64
